# gemm_out mainloop rewritten by hand (LDS-DMA 128-B row pieces, W double buffer + 5-slot U quarter ring) and its epilogue de-serialized (residual/gate loads hoisted before the k-loop, 16 stores without
# speedup vs baseline: 1.0966x; 1.0636x over previous
.LBB0_316:
	s_bfe_u32 s0, s9, 0xd0003
	s_mul_i32 s4, s0, 0x2493
	s_lshr_b32 s4, s4, 16
	s_mul_i32 s7, s4, 37
	s_lshr_b32 s8, s7, 8
	s_sub_i32 s8, s4, s8
	s_bfe_u32 s8, s8, 0x70001
	s_bfe_u32 s7, s7, 0x80008
	s_add_i32 s8, s8, s7
	s_bfe_u32 s7, s8, 0x60002
	s_mul_i32 s5, s4, 56
	s_mul_i32 s7, s7, 7
	s_sub_i32 s5, s9, s5
	s_sub_i32 s4, s4, s7
	s_and_b32 s6, s5, 0xffff
	s_mulk_i32 s0, 0xa73
	s_mul_i32 s4, s4, 7
	s_and_b32 s4, s4, 0xff
	s_bfe_u32 s16, s5, 0xd0003
	s_lshr_b32 s0, s0, 6
	s_lshl_b32 s8, s6, 8
	s_add_i32 s16, s16, s4
	s_and_b32 s0, s0, 0xf800
	s_and_b32 s4, s8, 0x700
	s_or_b32 s0, s4, s0
	s_lshl_b32 s4, s16, 19
	s_add_u32 s4, s12, s4
	s_addc_u32 s5, s13, 0
	s_lshl_b32 s6, s0, 12
	v_readlane_b32 s10, v254, 12
	v_readlane_b32 s11, v254, 13
	s_add_u32 s6, s10, s6
	s_addc_u32 s7, s11, 0
	v_lshrrev_b32_e32 v134, 6, v171
	v_and_b32_e32 v135, 63, v171
	v_readfirstlane_b32 s11, v134
	v_lshrrev_b32_e32 v175, 4, v135
	v_and_b32_e32 v128, 7, v135
	v_lshrrev_b32_e32 v129, 3, v135
	s_and_b32 s18, s11, 1
	s_lshl_b32 s18, s18, 2
	v_or_b32_e32 v176, s18, v175
	v_xor_b32_e32 v128, v128, v176
	v_lshlrev_b32_e32 v128, 4, v128
	v_lshl_or_b32 v128, v129, 12, v128
	s_lshl_b32 s18, s11, 15
	v_add_u32_e32 v128, s18, v128
	v_add_u32_e32 v129, 0x20000, v128
	v_add_u32_e32 v130, 0x40000, v128
	v_add_u32_e32 v131, 0x60000, v128
	v_add_u32_e32 v132, 0x80000, v128
	v_add_u32_e32 v133, 0xa0000, v128
	v_and_b32_e32 v134, 15, v135
	v_bfe_u32 v176, v134, 1, 3
	v_xor_b32_e32 v176, v176, v175
	v_lshlrev_b32_e32 v176, 4, v176
	v_lshl_or_b32 v176, v134, 7, v176
	s_and_b32 s18, s11, 1
	s_lshl_b32 s18, s18, 13
	v_add_u32_e32 v175, s18, v176
	s_lshr_b32 s19, s11, 1
	s_lshl_b32 s19, s19, 13
	v_add_u32_e32 v176, s19, v176
	v_xor_b32_e32 v177, 64, v175
	v_xor_b32_e32 v178, 64, v176
	s_lshl_b32 s11, s11, 10
	s_barrier
	s_add_u32 s18, s6, 0x40000
	s_addc_u32 s19, s7, 0
	s_add_u32 m0, s11, 0x4000
	s_nop 0
	global_load_lds_dwordx4 v128, s[6:7]
	s_add_u32 m0, s11, 0x5000
	s_nop 0
	global_load_lds_dwordx4 v129, s[6:7]
	s_add_u32 m0, s11, 0x6000
	s_nop 0
	global_load_lds_dwordx4 v132, s[6:7]
	s_add_u32 m0, s11, 0x7000
	s_nop 0
	global_load_lds_dwordx4 v133, s[6:7]
	s_add_u32 s6, s6, 128
	s_addc_u32 s7, s7, 0
	s_add_u32 m0, s11, 0x0
	s_nop 0
	global_load_lds_dwordx4 v128, s[4:5]
	s_add_u32 m0, s11, 0x1000
	s_nop 0
	global_load_lds_dwordx4 v129, s[4:5]
	s_add_u32 m0, s11, 0x2000
	s_nop 0
	global_load_lds_dwordx4 v130, s[4:5]
	s_add_u32 m0, s11, 0x3000
	s_nop 0
	global_load_lds_dwordx4 v131, s[4:5]
	s_add_u32 s4, s4, 128
	s_addc_u32 s5, s5, 0
	s_add_u32 m0, s11, 0x8000
	s_nop 0
	global_load_lds_dwordx4 v128, s[18:19]
	s_add_u32 m0, s11, 0x9000
	s_nop 0
	global_load_lds_dwordx4 v129, s[18:19]
	s_add_u32 m0, s11, 0xa000
	s_nop 0
	global_load_lds_dwordx4 v132, s[18:19]
	s_add_u32 m0, s11, 0xb000
	s_nop 0
	global_load_lds_dwordx4 v133, s[18:19]
	s_add_u32 s18, s18, 128
	s_addc_u32 s19, s19, 0
	v_mov_b32_e32 v0, 0
	v_mov_b32_e32 v1, v0
	v_mov_b32_e32 v2, v0
	v_mov_b32_e32 v3, v0
	v_mov_b32_e32 v4, v0
	v_mov_b32_e32 v5, v0
	v_mov_b32_e32 v6, v0
	v_mov_b32_e32 v7, v0
	v_mov_b32_e32 v8, v0
	v_mov_b32_e32 v9, v0
	v_mov_b32_e32 v10, v0
	v_mov_b32_e32 v11, v0
	v_mov_b32_e32 v12, v0
	v_mov_b32_e32 v13, v0
	v_mov_b32_e32 v14, v0
	v_mov_b32_e32 v15, v0
	v_mov_b32_e32 v16, v0
	v_mov_b32_e32 v17, v0
	v_mov_b32_e32 v18, v0
	v_mov_b32_e32 v19, v0
	v_mov_b32_e32 v20, v0
	v_mov_b32_e32 v21, v0
	v_mov_b32_e32 v22, v0
	v_mov_b32_e32 v23, v0
	v_mov_b32_e32 v24, v0
	v_mov_b32_e32 v25, v0
	v_mov_b32_e32 v26, v0
	v_mov_b32_e32 v27, v0
	v_mov_b32_e32 v28, v0
	v_mov_b32_e32 v29, v0
	v_mov_b32_e32 v30, v0
	v_mov_b32_e32 v31, v0
	v_mov_b32_e32 v32, v0
	v_mov_b32_e32 v33, v0
	v_mov_b32_e32 v34, v0
	v_mov_b32_e32 v35, v0
	v_mov_b32_e32 v36, v0
	v_mov_b32_e32 v37, v0
	v_mov_b32_e32 v38, v0
	v_mov_b32_e32 v39, v0
	v_mov_b32_e32 v40, v0
	v_mov_b32_e32 v41, v0
	v_mov_b32_e32 v42, v0
	v_mov_b32_e32 v43, v0
	v_mov_b32_e32 v44, v0
	v_mov_b32_e32 v45, v0
	v_mov_b32_e32 v46, v0
	v_mov_b32_e32 v47, v0
	v_mov_b32_e32 v48, v0
	v_mov_b32_e32 v49, v0
	v_mov_b32_e32 v50, v0
	v_mov_b32_e32 v51, v0
	v_mov_b32_e32 v52, v0
	v_mov_b32_e32 v53, v0
	v_mov_b32_e32 v54, v0
	v_mov_b32_e32 v55, v0
	v_mov_b32_e32 v56, v0
	v_mov_b32_e32 v57, v0
	v_mov_b32_e32 v58, v0
	v_mov_b32_e32 v59, v0
	v_mov_b32_e32 v60, v0
	v_mov_b32_e32 v61, v0
	v_mov_b32_e32 v62, v0
	v_mov_b32_e32 v63, v0
	v_mov_b32_e32 v64, v0
	v_mov_b32_e32 v65, v0
	v_mov_b32_e32 v66, v0
	v_mov_b32_e32 v67, v0
	v_mov_b32_e32 v68, v0
	v_mov_b32_e32 v69, v0
	v_mov_b32_e32 v70, v0
	v_mov_b32_e32 v71, v0
	v_mov_b32_e32 v72, v0
	v_mov_b32_e32 v73, v0
	v_mov_b32_e32 v74, v0
	v_mov_b32_e32 v75, v0
	v_mov_b32_e32 v76, v0
	v_mov_b32_e32 v77, v0
	v_mov_b32_e32 v78, v0
	v_mov_b32_e32 v79, v0
	v_mov_b32_e32 v80, v0
	v_mov_b32_e32 v81, v0
	v_mov_b32_e32 v82, v0
	v_mov_b32_e32 v83, v0
	v_mov_b32_e32 v84, v0
	v_mov_b32_e32 v85, v0
	v_mov_b32_e32 v86, v0
	v_mov_b32_e32 v87, v0
	v_mov_b32_e32 v88, v0
	v_mov_b32_e32 v89, v0
	v_mov_b32_e32 v90, v0
	v_mov_b32_e32 v91, v0
	v_mov_b32_e32 v92, v0
	v_mov_b32_e32 v93, v0
	v_mov_b32_e32 v94, v0
	v_mov_b32_e32 v95, v0
	v_mov_b32_e32 v96, v0
	v_mov_b32_e32 v97, v0
	v_mov_b32_e32 v98, v0
	v_mov_b32_e32 v99, v0
	v_mov_b32_e32 v100, v0
	v_mov_b32_e32 v101, v0
	v_mov_b32_e32 v102, v0
	v_mov_b32_e32 v103, v0
	v_mov_b32_e32 v104, v0
	v_mov_b32_e32 v105, v0
	v_mov_b32_e32 v106, v0
	v_mov_b32_e32 v107, v0
	v_mov_b32_e32 v108, v0
	v_mov_b32_e32 v109, v0
	v_mov_b32_e32 v110, v0
	v_mov_b32_e32 v111, v0
	v_mov_b32_e32 v112, v0
	v_mov_b32_e32 v113, v0
	v_mov_b32_e32 v114, v0
	v_mov_b32_e32 v115, v0
	v_mov_b32_e32 v116, v0
	v_mov_b32_e32 v117, v0
	v_mov_b32_e32 v118, v0
	v_mov_b32_e32 v119, v0
	v_mov_b32_e32 v120, v0
	v_mov_b32_e32 v121, v0
	v_mov_b32_e32 v122, v0
	v_mov_b32_e32 v123, v0
	v_mov_b32_e32 v124, v0
	v_mov_b32_e32 v125, v0
	v_mov_b32_e32 v126, v0
	v_mov_b32_e32 v127, v0
	s_mov_b32 s10, 0
.Lgin_loop:
	s_waitcnt vmcnt(4)
	s_barrier
	ds_read_b128 v[230:233], v175 offset:0
	ds_read_b128 v[234:237], v175 offset:2048
	ds_read_b128 v[238:241], v175 offset:4096
	ds_read_b128 v[242:245], v175 offset:6144
	ds_read_b128 v[136:139], v177 offset:0
	ds_read_b128 v[140:143], v177 offset:2048
	ds_read_b128 v[144:147], v177 offset:4096
	ds_read_b128 v[148:151], v177 offset:6144
	ds_read_b128 v[182:185], v176 offset:16384
	ds_read_b128 v[186:189], v176 offset:18432
	ds_read_b128 v[190:193], v176 offset:20480
	ds_read_b128 v[194:197], v176 offset:22528
	s_add_u32 m0, s11, 0xc000
	s_waitcnt lgkmcnt(3)
	v_mfma_f32_16x16x32_f16 v[124:127], v[230:233], v[182:185], v[124:127]
	v_mfma_f32_16x16x32_f16 v[92:95], v[234:237], v[182:185], v[92:95]
	v_mfma_f32_16x16x32_f16 v[60:63], v[238:241], v[182:185], v[60:63]
	v_mfma_f32_16x16x32_f16 v[28:31], v[242:245], v[182:185], v[28:31]
	global_load_lds_dwordx4 v128, s[6:7]
	s_barrier
	ds_read_b128 v[198:201], v178 offset:16384
	ds_read_b128 v[202:205], v178 offset:18432
	ds_read_b128 v[222:225], v178 offset:20480
	ds_read_b128 v[226:229], v178 offset:22528
	s_add_u32 m0, s11, 0xd000
	s_waitcnt lgkmcnt(6)
	v_mfma_f32_16x16x32_f16 v[120:123], v[230:233], v[186:189], v[120:123]
	v_mfma_f32_16x16x32_f16 v[88:91], v[234:237], v[186:189], v[88:91]
	v_mfma_f32_16x16x32_f16 v[56:59], v[238:241], v[186:189], v[56:59]
	v_mfma_f32_16x16x32_f16 v[24:27], v[242:245], v[186:189], v[24:27]
	global_load_lds_dwordx4 v129, s[6:7]
	s_add_u32 m0, s11, 0xe000
	s_waitcnt lgkmcnt(5)
	v_mfma_f32_16x16x32_f16 v[116:119], v[230:233], v[190:193], v[116:119]
	v_mfma_f32_16x16x32_f16 v[84:87], v[234:237], v[190:193], v[84:87]
	v_mfma_f32_16x16x32_f16 v[52:55], v[238:241], v[190:193], v[52:55]
	v_mfma_f32_16x16x32_f16 v[20:23], v[242:245], v[190:193], v[20:23]
	global_load_lds_dwordx4 v132, s[6:7]
	s_add_u32 m0, s11, 0xf000
	s_waitcnt lgkmcnt(4)
	v_mfma_f32_16x16x32_f16 v[112:115], v[230:233], v[194:197], v[112:115]
	v_mfma_f32_16x16x32_f16 v[80:83], v[234:237], v[194:197], v[80:83]
	v_mfma_f32_16x16x32_f16 v[48:51], v[238:241], v[194:197], v[48:51]
	v_mfma_f32_16x16x32_f16 v[16:19], v[242:245], v[194:197], v[16:19]
	global_load_lds_dwordx4 v133, s[6:7]
	s_add_u32 m0, s11, 0x0
	s_waitcnt lgkmcnt(3)
	v_mfma_f32_16x16x32_f16 v[124:127], v[136:139], v[198:201], v[124:127]
	v_mfma_f32_16x16x32_f16 v[92:95], v[140:143], v[198:201], v[92:95]
	v_mfma_f32_16x16x32_f16 v[60:63], v[144:147], v[198:201], v[60:63]
	v_mfma_f32_16x16x32_f16 v[28:31], v[148:151], v[198:201], v[28:31]
	global_load_lds_dwordx4 v128, s[4:5]
	s_add_u32 m0, s11, 0x1000
	s_waitcnt lgkmcnt(2)
	v_mfma_f32_16x16x32_f16 v[120:123], v[136:139], v[202:205], v[120:123]
	v_mfma_f32_16x16x32_f16 v[88:91], v[140:143], v[202:205], v[88:91]
	v_mfma_f32_16x16x32_f16 v[56:59], v[144:147], v[202:205], v[56:59]
	v_mfma_f32_16x16x32_f16 v[24:27], v[148:151], v[202:205], v[24:27]
	global_load_lds_dwordx4 v129, s[4:5]
	s_add_u32 m0, s11, 0x2000
	s_waitcnt lgkmcnt(1)
	v_mfma_f32_16x16x32_f16 v[116:119], v[136:139], v[222:225], v[116:119]
	v_mfma_f32_16x16x32_f16 v[84:87], v[140:143], v[222:225], v[84:87]
	v_mfma_f32_16x16x32_f16 v[52:55], v[144:147], v[222:225], v[52:55]
	v_mfma_f32_16x16x32_f16 v[20:23], v[148:151], v[222:225], v[20:23]
	global_load_lds_dwordx4 v130, s[4:5]
	s_add_u32 m0, s11, 0x3000
	s_waitcnt lgkmcnt(0)
	v_mfma_f32_16x16x32_f16 v[112:115], v[136:139], v[226:229], v[112:115]
	v_mfma_f32_16x16x32_f16 v[80:83], v[140:143], v[226:229], v[80:83]
	v_mfma_f32_16x16x32_f16 v[48:51], v[144:147], v[226:229], v[48:51]
	v_mfma_f32_16x16x32_f16 v[16:19], v[148:151], v[226:229], v[16:19]
	global_load_lds_dwordx4 v131, s[4:5]
	s_add_u32 s6, s6, 128
	s_addc_u32 s7, s7, 0
	s_add_u32 s4, s4, 128
	s_addc_u32 s5, s5, 0
	s_waitcnt vmcnt(8)
	s_barrier
	ds_read_b128 v[182:185], v176 offset:32768
	ds_read_b128 v[186:189], v176 offset:34816
	ds_read_b128 v[190:193], v176 offset:36864
	ds_read_b128 v[194:197], v176 offset:38912
	ds_read_b128 v[198:201], v178 offset:32768
	ds_read_b128 v[202:205], v178 offset:34816
	ds_read_b128 v[222:225], v178 offset:36864
	ds_read_b128 v[226:229], v178 offset:38912
	s_add_u32 m0, s11, 0x4000
	s_waitcnt lgkmcnt(7)
	v_mfma_f32_16x16x32_f16 v[108:111], v[230:233], v[182:185], v[108:111]
	v_mfma_f32_16x16x32_f16 v[76:79], v[234:237], v[182:185], v[76:79]
	v_mfma_f32_16x16x32_f16 v[44:47], v[238:241], v[182:185], v[44:47]
	v_mfma_f32_16x16x32_f16 v[12:15], v[242:245], v[182:185], v[12:15]
	global_load_lds_dwordx4 v128, s[18:19]
	s_add_u32 m0, s11, 0x5000
	s_waitcnt lgkmcnt(6)
	v_mfma_f32_16x16x32_f16 v[104:107], v[230:233], v[186:189], v[104:107]
	v_mfma_f32_16x16x32_f16 v[72:75], v[234:237], v[186:189], v[72:75]
	v_mfma_f32_16x16x32_f16 v[40:43], v[238:241], v[186:189], v[40:43]
	v_mfma_f32_16x16x32_f16 v[8:11], v[242:245], v[186:189], v[8:11]
	global_load_lds_dwordx4 v129, s[18:19]
	s_add_u32 m0, s11, 0x6000
	s_waitcnt lgkmcnt(5)
	v_mfma_f32_16x16x32_f16 v[100:103], v[230:233], v[190:193], v[100:103]
	v_mfma_f32_16x16x32_f16 v[68:71], v[234:237], v[190:193], v[68:71]
	v_mfma_f32_16x16x32_f16 v[36:39], v[238:241], v[190:193], v[36:39]
	v_mfma_f32_16x16x32_f16 v[4:7], v[242:245], v[190:193], v[4:7]
	global_load_lds_dwordx4 v132, s[18:19]
	s_add_u32 m0, s11, 0x7000
	s_waitcnt lgkmcnt(4)
	v_mfma_f32_16x16x32_f16 v[96:99], v[230:233], v[194:197], v[96:99]
	v_mfma_f32_16x16x32_f16 v[64:67], v[234:237], v[194:197], v[64:67]
	v_mfma_f32_16x16x32_f16 v[32:35], v[238:241], v[194:197], v[32:35]
	v_mfma_f32_16x16x32_f16 v[0:3], v[242:245], v[194:197], v[0:3]
	global_load_lds_dwordx4 v133, s[18:19]
	s_waitcnt lgkmcnt(3)
	v_mfma_f32_16x16x32_f16 v[108:111], v[136:139], v[198:201], v[108:111]
	v_mfma_f32_16x16x32_f16 v[76:79], v[140:143], v[198:201], v[76:79]
	v_mfma_f32_16x16x32_f16 v[44:47], v[144:147], v[198:201], v[44:47]
	v_mfma_f32_16x16x32_f16 v[12:15], v[148:151], v[198:201], v[12:15]
	s_waitcnt lgkmcnt(2)
	v_mfma_f32_16x16x32_f16 v[104:107], v[136:139], v[202:205], v[104:107]
	v_mfma_f32_16x16x32_f16 v[72:75], v[140:143], v[202:205], v[72:75]
	v_mfma_f32_16x16x32_f16 v[40:43], v[144:147], v[202:205], v[40:43]
	v_mfma_f32_16x16x32_f16 v[8:11], v[148:151], v[202:205], v[8:11]
	s_waitcnt lgkmcnt(1)
	v_mfma_f32_16x16x32_f16 v[100:103], v[136:139], v[222:225], v[100:103]
	v_mfma_f32_16x16x32_f16 v[68:71], v[140:143], v[222:225], v[68:71]
	v_mfma_f32_16x16x32_f16 v[36:39], v[144:147], v[222:225], v[36:39]
	v_mfma_f32_16x16x32_f16 v[4:7], v[148:151], v[222:225], v[4:7]
	s_waitcnt lgkmcnt(0)
	v_mfma_f32_16x16x32_f16 v[96:99], v[136:139], v[226:229], v[96:99]
	v_mfma_f32_16x16x32_f16 v[64:67], v[140:143], v[226:229], v[64:67]
	v_mfma_f32_16x16x32_f16 v[32:35], v[144:147], v[226:229], v[32:35]
	v_mfma_f32_16x16x32_f16 v[0:3], v[148:151], v[226:229], v[0:3]
	s_add_u32 s18, s18, 128
	s_addc_u32 s19, s19, 0
	s_waitcnt vmcnt(4)
	s_barrier
	ds_read_b128 v[230:233], v175 offset:0
	ds_read_b128 v[234:237], v175 offset:2048
	ds_read_b128 v[238:241], v175 offset:4096
	ds_read_b128 v[242:245], v175 offset:6144
	ds_read_b128 v[136:139], v177 offset:0
	ds_read_b128 v[140:143], v177 offset:2048
	ds_read_b128 v[144:147], v177 offset:4096
	ds_read_b128 v[148:151], v177 offset:6144
	ds_read_b128 v[182:185], v176 offset:49152
	ds_read_b128 v[186:189], v176 offset:51200
	ds_read_b128 v[190:193], v176 offset:53248
	ds_read_b128 v[194:197], v176 offset:55296
	s_add_u32 m0, s11, 0x8000
	s_waitcnt lgkmcnt(3)
	v_mfma_f32_16x16x32_f16 v[124:127], v[230:233], v[182:185], v[124:127]
	v_mfma_f32_16x16x32_f16 v[92:95], v[234:237], v[182:185], v[92:95]
	v_mfma_f32_16x16x32_f16 v[60:63], v[238:241], v[182:185], v[60:63]
	v_mfma_f32_16x16x32_f16 v[28:31], v[242:245], v[182:185], v[28:31]
	global_load_lds_dwordx4 v128, s[6:7]
	s_barrier
	ds_read_b128 v[198:201], v178 offset:49152
	ds_read_b128 v[202:205], v178 offset:51200
	ds_read_b128 v[222:225], v178 offset:53248
	ds_read_b128 v[226:229], v178 offset:55296
	s_add_u32 m0, s11, 0x9000
	s_waitcnt lgkmcnt(6)
	v_mfma_f32_16x16x32_f16 v[120:123], v[230:233], v[186:189], v[120:123]
	v_mfma_f32_16x16x32_f16 v[88:91], v[234:237], v[186:189], v[88:91]
	v_mfma_f32_16x16x32_f16 v[56:59], v[238:241], v[186:189], v[56:59]
	v_mfma_f32_16x16x32_f16 v[24:27], v[242:245], v[186:189], v[24:27]
	global_load_lds_dwordx4 v129, s[6:7]
	s_add_u32 m0, s11, 0xa000
	s_waitcnt lgkmcnt(5)
	v_mfma_f32_16x16x32_f16 v[116:119], v[230:233], v[190:193], v[116:119]
	v_mfma_f32_16x16x32_f16 v[84:87], v[234:237], v[190:193], v[84:87]
	v_mfma_f32_16x16x32_f16 v[52:55], v[238:241], v[190:193], v[52:55]
	v_mfma_f32_16x16x32_f16 v[20:23], v[242:245], v[190:193], v[20:23]
	global_load_lds_dwordx4 v132, s[6:7]
	s_add_u32 m0, s11, 0xb000
	s_waitcnt lgkmcnt(4)
	v_mfma_f32_16x16x32_f16 v[112:115], v[230:233], v[194:197], v[112:115]
	v_mfma_f32_16x16x32_f16 v[80:83], v[234:237], v[194:197], v[80:83]
	v_mfma_f32_16x16x32_f16 v[48:51], v[238:241], v[194:197], v[48:51]
	v_mfma_f32_16x16x32_f16 v[16:19], v[242:245], v[194:197], v[16:19]
	global_load_lds_dwordx4 v133, s[6:7]
	s_add_u32 m0, s11, 0x0
	s_waitcnt lgkmcnt(3)
	v_mfma_f32_16x16x32_f16 v[124:127], v[136:139], v[198:201], v[124:127]
	v_mfma_f32_16x16x32_f16 v[92:95], v[140:143], v[198:201], v[92:95]
	v_mfma_f32_16x16x32_f16 v[60:63], v[144:147], v[198:201], v[60:63]
	v_mfma_f32_16x16x32_f16 v[28:31], v[148:151], v[198:201], v[28:31]
	global_load_lds_dwordx4 v128, s[4:5]
	s_add_u32 m0, s11, 0x1000
	s_waitcnt lgkmcnt(2)
	v_mfma_f32_16x16x32_f16 v[120:123], v[136:139], v[202:205], v[120:123]
	v_mfma_f32_16x16x32_f16 v[88:91], v[140:143], v[202:205], v[88:91]
	v_mfma_f32_16x16x32_f16 v[56:59], v[144:147], v[202:205], v[56:59]
	v_mfma_f32_16x16x32_f16 v[24:27], v[148:151], v[202:205], v[24:27]
	global_load_lds_dwordx4 v129, s[4:5]
	s_add_u32 m0, s11, 0x2000
	s_waitcnt lgkmcnt(1)
	v_mfma_f32_16x16x32_f16 v[116:119], v[136:139], v[222:225], v[116:119]
	v_mfma_f32_16x16x32_f16 v[84:87], v[140:143], v[222:225], v[84:87]
	v_mfma_f32_16x16x32_f16 v[52:55], v[144:147], v[222:225], v[52:55]
	v_mfma_f32_16x16x32_f16 v[20:23], v[148:151], v[222:225], v[20:23]
	global_load_lds_dwordx4 v130, s[4:5]
	s_add_u32 m0, s11, 0x3000
	s_waitcnt lgkmcnt(0)
	v_mfma_f32_16x16x32_f16 v[112:115], v[136:139], v[226:229], v[112:115]
	v_mfma_f32_16x16x32_f16 v[80:83], v[140:143], v[226:229], v[80:83]
	v_mfma_f32_16x16x32_f16 v[48:51], v[144:147], v[226:229], v[48:51]
	v_mfma_f32_16x16x32_f16 v[16:19], v[148:151], v[226:229], v[16:19]
	global_load_lds_dwordx4 v131, s[4:5]
	s_add_u32 s6, s6, 128
	s_addc_u32 s7, s7, 0
	s_add_u32 s4, s4, 128
	s_addc_u32 s5, s5, 0
	s_waitcnt vmcnt(8)
	s_barrier
	ds_read_b128 v[182:185], v176 offset:16384
	ds_read_b128 v[186:189], v176 offset:18432
	ds_read_b128 v[190:193], v176 offset:20480
	ds_read_b128 v[194:197], v176 offset:22528
	ds_read_b128 v[198:201], v178 offset:16384
	ds_read_b128 v[202:205], v178 offset:18432
	ds_read_b128 v[222:225], v178 offset:20480
	ds_read_b128 v[226:229], v178 offset:22528
	s_add_u32 m0, s11, 0xc000
	s_waitcnt lgkmcnt(7)
	v_mfma_f32_16x16x32_f16 v[108:111], v[230:233], v[182:185], v[108:111]
	v_mfma_f32_16x16x32_f16 v[76:79], v[234:237], v[182:185], v[76:79]
	v_mfma_f32_16x16x32_f16 v[44:47], v[238:241], v[182:185], v[44:47]
	v_mfma_f32_16x16x32_f16 v[12:15], v[242:245], v[182:185], v[12:15]
	global_load_lds_dwordx4 v128, s[18:19]
	s_add_u32 m0, s11, 0xd000
	s_waitcnt lgkmcnt(6)
	v_mfma_f32_16x16x32_f16 v[104:107], v[230:233], v[186:189], v[104:107]
	v_mfma_f32_16x16x32_f16 v[72:75], v[234:237], v[186:189], v[72:75]
	v_mfma_f32_16x16x32_f16 v[40:43], v[238:241], v[186:189], v[40:43]
	v_mfma_f32_16x16x32_f16 v[8:11], v[242:245], v[186:189], v[8:11]
	global_load_lds_dwordx4 v129, s[18:19]
	s_add_u32 m0, s11, 0xe000
	s_waitcnt lgkmcnt(5)
	v_mfma_f32_16x16x32_f16 v[100:103], v[230:233], v[190:193], v[100:103]
	v_mfma_f32_16x16x32_f16 v[68:71], v[234:237], v[190:193], v[68:71]
	v_mfma_f32_16x16x32_f16 v[36:39], v[238:241], v[190:193], v[36:39]
	v_mfma_f32_16x16x32_f16 v[4:7], v[242:245], v[190:193], v[4:7]
	global_load_lds_dwordx4 v132, s[18:19]
	s_add_u32 m0, s11, 0xf000
	s_waitcnt lgkmcnt(4)
	v_mfma_f32_16x16x32_f16 v[96:99], v[230:233], v[194:197], v[96:99]
	v_mfma_f32_16x16x32_f16 v[64:67], v[234:237], v[194:197], v[64:67]
	v_mfma_f32_16x16x32_f16 v[32:35], v[238:241], v[194:197], v[32:35]
	v_mfma_f32_16x16x32_f16 v[0:3], v[242:245], v[194:197], v[0:3]
	global_load_lds_dwordx4 v133, s[18:19]
	s_waitcnt lgkmcnt(3)
	v_mfma_f32_16x16x32_f16 v[108:111], v[136:139], v[198:201], v[108:111]
	v_mfma_f32_16x16x32_f16 v[76:79], v[140:143], v[198:201], v[76:79]
	v_mfma_f32_16x16x32_f16 v[44:47], v[144:147], v[198:201], v[44:47]
	v_mfma_f32_16x16x32_f16 v[12:15], v[148:151], v[198:201], v[12:15]
	s_waitcnt lgkmcnt(2)
	v_mfma_f32_16x16x32_f16 v[104:107], v[136:139], v[202:205], v[104:107]
	v_mfma_f32_16x16x32_f16 v[72:75], v[140:143], v[202:205], v[72:75]
	v_mfma_f32_16x16x32_f16 v[40:43], v[144:147], v[202:205], v[40:43]
	v_mfma_f32_16x16x32_f16 v[8:11], v[148:151], v[202:205], v[8:11]
	s_waitcnt lgkmcnt(1)
	v_mfma_f32_16x16x32_f16 v[100:103], v[136:139], v[222:225], v[100:103]
	v_mfma_f32_16x16x32_f16 v[68:71], v[140:143], v[222:225], v[68:71]
	v_mfma_f32_16x16x32_f16 v[36:39], v[144:147], v[222:225], v[36:39]
	v_mfma_f32_16x16x32_f16 v[4:7], v[148:151], v[222:225], v[4:7]
	s_waitcnt lgkmcnt(0)
	v_mfma_f32_16x16x32_f16 v[96:99], v[136:139], v[226:229], v[96:99]
	v_mfma_f32_16x16x32_f16 v[64:67], v[140:143], v[226:229], v[64:67]
	v_mfma_f32_16x16x32_f16 v[32:35], v[144:147], v[226:229], v[32:35]
	v_mfma_f32_16x16x32_f16 v[0:3], v[148:151], v[226:229], v[0:3]
	s_add_u32 s18, s18, 128
	s_addc_u32 s19, s19, 0
	s_waitcnt vmcnt(4)
	s_barrier
	ds_read_b128 v[230:233], v175 offset:0
	ds_read_b128 v[234:237], v175 offset:2048
	ds_read_b128 v[238:241], v175 offset:4096
	ds_read_b128 v[242:245], v175 offset:6144
	ds_read_b128 v[136:139], v177 offset:0
	ds_read_b128 v[140:143], v177 offset:2048
	ds_read_b128 v[144:147], v177 offset:4096
	ds_read_b128 v[148:151], v177 offset:6144
	ds_read_b128 v[182:185], v176 offset:32768
	ds_read_b128 v[186:189], v176 offset:34816
	ds_read_b128 v[190:193], v176 offset:36864
	ds_read_b128 v[194:197], v176 offset:38912
	s_add_u32 m0, s11, 0x4000
	s_waitcnt lgkmcnt(3)
	v_mfma_f32_16x16x32_f16 v[124:127], v[230:233], v[182:185], v[124:127]
	v_mfma_f32_16x16x32_f16 v[92:95], v[234:237], v[182:185], v[92:95]
	v_mfma_f32_16x16x32_f16 v[60:63], v[238:241], v[182:185], v[60:63]
	v_mfma_f32_16x16x32_f16 v[28:31], v[242:245], v[182:185], v[28:31]
	global_load_lds_dwordx4 v128, s[6:7]
	s_barrier
	ds_read_b128 v[198:201], v178 offset:32768
	ds_read_b128 v[202:205], v178 offset:34816
	ds_read_b128 v[222:225], v178 offset:36864
	ds_read_b128 v[226:229], v178 offset:38912
	s_add_u32 m0, s11, 0x5000
	s_waitcnt lgkmcnt(6)
	v_mfma_f32_16x16x32_f16 v[120:123], v[230:233], v[186:189], v[120:123]
	v_mfma_f32_16x16x32_f16 v[88:91], v[234:237], v[186:189], v[88:91]
	v_mfma_f32_16x16x32_f16 v[56:59], v[238:241], v[186:189], v[56:59]
	v_mfma_f32_16x16x32_f16 v[24:27], v[242:245], v[186:189], v[24:27]
	global_load_lds_dwordx4 v129, s[6:7]
	s_add_u32 m0, s11, 0x6000
	s_waitcnt lgkmcnt(5)
	v_mfma_f32_16x16x32_f16 v[116:119], v[230:233], v[190:193], v[116:119]
	v_mfma_f32_16x16x32_f16 v[84:87], v[234:237], v[190:193], v[84:87]
	v_mfma_f32_16x16x32_f16 v[52:55], v[238:241], v[190:193], v[52:55]
	v_mfma_f32_16x16x32_f16 v[20:23], v[242:245], v[190:193], v[20:23]
	global_load_lds_dwordx4 v132, s[6:7]
	s_add_u32 m0, s11, 0x7000
	s_waitcnt lgkmcnt(4)
	v_mfma_f32_16x16x32_f16 v[112:115], v[230:233], v[194:197], v[112:115]
	v_mfma_f32_16x16x32_f16 v[80:83], v[234:237], v[194:197], v[80:83]
	v_mfma_f32_16x16x32_f16 v[48:51], v[238:241], v[194:197], v[48:51]
	v_mfma_f32_16x16x32_f16 v[16:19], v[242:245], v[194:197], v[16:19]
	global_load_lds_dwordx4 v133, s[6:7]
	s_add_u32 m0, s11, 0x0
	s_waitcnt lgkmcnt(3)
	v_mfma_f32_16x16x32_f16 v[124:127], v[136:139], v[198:201], v[124:127]
	v_mfma_f32_16x16x32_f16 v[92:95], v[140:143], v[198:201], v[92:95]
	v_mfma_f32_16x16x32_f16 v[60:63], v[144:147], v[198:201], v[60:63]
	v_mfma_f32_16x16x32_f16 v[28:31], v[148:151], v[198:201], v[28:31]
	global_load_lds_dwordx4 v128, s[4:5]
	s_add_u32 m0, s11, 0x1000
	s_waitcnt lgkmcnt(2)
	v_mfma_f32_16x16x32_f16 v[120:123], v[136:139], v[202:205], v[120:123]
	v_mfma_f32_16x16x32_f16 v[88:91], v[140:143], v[202:205], v[88:91]
	v_mfma_f32_16x16x32_f16 v[56:59], v[144:147], v[202:205], v[56:59]
	v_mfma_f32_16x16x32_f16 v[24:27], v[148:151], v[202:205], v[24:27]
	global_load_lds_dwordx4 v129, s[4:5]
	s_add_u32 m0, s11, 0x2000
	s_waitcnt lgkmcnt(1)
	v_mfma_f32_16x16x32_f16 v[116:119], v[136:139], v[222:225], v[116:119]
	v_mfma_f32_16x16x32_f16 v[84:87], v[140:143], v[222:225], v[84:87]
	v_mfma_f32_16x16x32_f16 v[52:55], v[144:147], v[222:225], v[52:55]
	v_mfma_f32_16x16x32_f16 v[20:23], v[148:151], v[222:225], v[20:23]
	global_load_lds_dwordx4 v130, s[4:5]
	s_add_u32 m0, s11, 0x3000
	s_waitcnt lgkmcnt(0)
	v_mfma_f32_16x16x32_f16 v[112:115], v[136:139], v[226:229], v[112:115]
	v_mfma_f32_16x16x32_f16 v[80:83], v[140:143], v[226:229], v[80:83]
	v_mfma_f32_16x16x32_f16 v[48:51], v[144:147], v[226:229], v[48:51]
	v_mfma_f32_16x16x32_f16 v[16:19], v[148:151], v[226:229], v[16:19]
	global_load_lds_dwordx4 v131, s[4:5]
	s_add_u32 s6, s6, 128
	s_addc_u32 s7, s7, 0
	s_add_u32 s4, s4, 128
	s_addc_u32 s5, s5, 0
	s_waitcnt vmcnt(8)
	s_barrier
	ds_read_b128 v[182:185], v176 offset:49152
	ds_read_b128 v[186:189], v176 offset:51200
	ds_read_b128 v[190:193], v176 offset:53248
	ds_read_b128 v[194:197], v176 offset:55296
	ds_read_b128 v[198:201], v178 offset:49152
	ds_read_b128 v[202:205], v178 offset:51200
	ds_read_b128 v[222:225], v178 offset:53248
	ds_read_b128 v[226:229], v178 offset:55296
	s_add_u32 m0, s11, 0x8000
	s_waitcnt lgkmcnt(7)
	v_mfma_f32_16x16x32_f16 v[108:111], v[230:233], v[182:185], v[108:111]
	v_mfma_f32_16x16x32_f16 v[76:79], v[234:237], v[182:185], v[76:79]
	v_mfma_f32_16x16x32_f16 v[44:47], v[238:241], v[182:185], v[44:47]
	v_mfma_f32_16x16x32_f16 v[12:15], v[242:245], v[182:185], v[12:15]
	global_load_lds_dwordx4 v128, s[18:19]
	s_add_u32 m0, s11, 0x9000
	s_waitcnt lgkmcnt(6)
	v_mfma_f32_16x16x32_f16 v[104:107], v[230:233], v[186:189], v[104:107]
	v_mfma_f32_16x16x32_f16 v[72:75], v[234:237], v[186:189], v[72:75]
	v_mfma_f32_16x16x32_f16 v[40:43], v[238:241], v[186:189], v[40:43]
	v_mfma_f32_16x16x32_f16 v[8:11], v[242:245], v[186:189], v[8:11]
	global_load_lds_dwordx4 v129, s[18:19]
	s_add_u32 m0, s11, 0xa000
	s_waitcnt lgkmcnt(5)
	v_mfma_f32_16x16x32_f16 v[100:103], v[230:233], v[190:193], v[100:103]
	v_mfma_f32_16x16x32_f16 v[68:71], v[234:237], v[190:193], v[68:71]
	v_mfma_f32_16x16x32_f16 v[36:39], v[238:241], v[190:193], v[36:39]
	v_mfma_f32_16x16x32_f16 v[4:7], v[242:245], v[190:193], v[4:7]
	global_load_lds_dwordx4 v132, s[18:19]
	s_add_u32 m0, s11, 0xb000
	s_waitcnt lgkmcnt(4)
	v_mfma_f32_16x16x32_f16 v[96:99], v[230:233], v[194:197], v[96:99]
	v_mfma_f32_16x16x32_f16 v[64:67], v[234:237], v[194:197], v[64:67]
	v_mfma_f32_16x16x32_f16 v[32:35], v[238:241], v[194:197], v[32:35]
	v_mfma_f32_16x16x32_f16 v[0:3], v[242:245], v[194:197], v[0:3]
	global_load_lds_dwordx4 v133, s[18:19]
	s_waitcnt lgkmcnt(3)
	v_mfma_f32_16x16x32_f16 v[108:111], v[136:139], v[198:201], v[108:111]
	v_mfma_f32_16x16x32_f16 v[76:79], v[140:143], v[198:201], v[76:79]
	v_mfma_f32_16x16x32_f16 v[44:47], v[144:147], v[198:201], v[44:47]
	v_mfma_f32_16x16x32_f16 v[12:15], v[148:151], v[198:201], v[12:15]
	s_waitcnt lgkmcnt(2)
	v_mfma_f32_16x16x32_f16 v[104:107], v[136:139], v[202:205], v[104:107]
	v_mfma_f32_16x16x32_f16 v[72:75], v[140:143], v[202:205], v[72:75]
	v_mfma_f32_16x16x32_f16 v[40:43], v[144:147], v[202:205], v[40:43]
	v_mfma_f32_16x16x32_f16 v[8:11], v[148:151], v[202:205], v[8:11]
	s_waitcnt lgkmcnt(1)
	v_mfma_f32_16x16x32_f16 v[100:103], v[136:139], v[222:225], v[100:103]
	v_mfma_f32_16x16x32_f16 v[68:71], v[140:143], v[222:225], v[68:71]
	v_mfma_f32_16x16x32_f16 v[36:39], v[144:147], v[222:225], v[36:39]
	v_mfma_f32_16x16x32_f16 v[4:7], v[148:151], v[222:225], v[4:7]
	s_waitcnt lgkmcnt(0)
	v_mfma_f32_16x16x32_f16 v[96:99], v[136:139], v[226:229], v[96:99]
	v_mfma_f32_16x16x32_f16 v[64:67], v[140:143], v[226:229], v[64:67]
	v_mfma_f32_16x16x32_f16 v[32:35], v[144:147], v[226:229], v[32:35]
	v_mfma_f32_16x16x32_f16 v[0:3], v[148:151], v[226:229], v[0:3]
	s_add_u32 s18, s18, 128
	s_addc_u32 s19, s19, 0
	s_add_i32 s10, s10, 1
	s_cmp_lt_u32 s10, 10
	s_cbranch_scc1 .Lgin_loop
	s_waitcnt vmcnt(4)
	s_barrier
	ds_read_b128 v[230:233], v175 offset:0
	ds_read_b128 v[234:237], v175 offset:2048
	ds_read_b128 v[238:241], v175 offset:4096
	ds_read_b128 v[242:245], v175 offset:6144
	ds_read_b128 v[136:139], v177 offset:0
	ds_read_b128 v[140:143], v177 offset:2048
	ds_read_b128 v[144:147], v177 offset:4096
	ds_read_b128 v[148:151], v177 offset:6144
	ds_read_b128 v[182:185], v176 offset:16384
	ds_read_b128 v[186:189], v176 offset:18432
	ds_read_b128 v[190:193], v176 offset:20480
	ds_read_b128 v[194:197], v176 offset:22528
	s_add_u32 m0, s11, 0xc000
	s_waitcnt lgkmcnt(3)
	v_mfma_f32_16x16x32_f16 v[124:127], v[230:233], v[182:185], v[124:127]
	v_mfma_f32_16x16x32_f16 v[92:95], v[234:237], v[182:185], v[92:95]
	v_mfma_f32_16x16x32_f16 v[60:63], v[238:241], v[182:185], v[60:63]
	v_mfma_f32_16x16x32_f16 v[28:31], v[242:245], v[182:185], v[28:31]
	global_load_lds_dwordx4 v128, s[6:7]
	s_barrier
	ds_read_b128 v[198:201], v178 offset:16384
	ds_read_b128 v[202:205], v178 offset:18432
	ds_read_b128 v[222:225], v178 offset:20480
	ds_read_b128 v[226:229], v178 offset:22528
	s_add_u32 m0, s11, 0xd000
	s_waitcnt lgkmcnt(6)
	v_mfma_f32_16x16x32_f16 v[120:123], v[230:233], v[186:189], v[120:123]
	v_mfma_f32_16x16x32_f16 v[88:91], v[234:237], v[186:189], v[88:91]
	v_mfma_f32_16x16x32_f16 v[56:59], v[238:241], v[186:189], v[56:59]
	v_mfma_f32_16x16x32_f16 v[24:27], v[242:245], v[186:189], v[24:27]
	global_load_lds_dwordx4 v129, s[6:7]
	s_add_u32 m0, s11, 0xe000
	s_waitcnt lgkmcnt(5)
	v_mfma_f32_16x16x32_f16 v[116:119], v[230:233], v[190:193], v[116:119]
	v_mfma_f32_16x16x32_f16 v[84:87], v[234:237], v[190:193], v[84:87]
	v_mfma_f32_16x16x32_f16 v[52:55], v[238:241], v[190:193], v[52:55]
	v_mfma_f32_16x16x32_f16 v[20:23], v[242:245], v[190:193], v[20:23]
	global_load_lds_dwordx4 v132, s[6:7]
	s_add_u32 m0, s11, 0xf000
	s_waitcnt lgkmcnt(4)
	v_mfma_f32_16x16x32_f16 v[112:115], v[230:233], v[194:197], v[112:115]
	v_mfma_f32_16x16x32_f16 v[80:83], v[234:237], v[194:197], v[80:83]
	v_mfma_f32_16x16x32_f16 v[48:51], v[238:241], v[194:197], v[48:51]
	v_mfma_f32_16x16x32_f16 v[16:19], v[242:245], v[194:197], v[16:19]
	global_load_lds_dwordx4 v133, s[6:7]
	s_add_u32 m0, s11, 0x0
	s_waitcnt lgkmcnt(3)
	v_mfma_f32_16x16x32_f16 v[124:127], v[136:139], v[198:201], v[124:127]
	v_mfma_f32_16x16x32_f16 v[92:95], v[140:143], v[198:201], v[92:95]
	v_mfma_f32_16x16x32_f16 v[60:63], v[144:147], v[198:201], v[60:63]
	v_mfma_f32_16x16x32_f16 v[28:31], v[148:151], v[198:201], v[28:31]
	global_load_lds_dwordx4 v128, s[4:5]
	s_add_u32 m0, s11, 0x1000
	s_waitcnt lgkmcnt(2)
	v_mfma_f32_16x16x32_f16 v[120:123], v[136:139], v[202:205], v[120:123]
	v_mfma_f32_16x16x32_f16 v[88:91], v[140:143], v[202:205], v[88:91]
	v_mfma_f32_16x16x32_f16 v[56:59], v[144:147], v[202:205], v[56:59]
	v_mfma_f32_16x16x32_f16 v[24:27], v[148:151], v[202:205], v[24:27]
	global_load_lds_dwordx4 v129, s[4:5]
	s_add_u32 m0, s11, 0x2000
	s_waitcnt lgkmcnt(1)
	v_mfma_f32_16x16x32_f16 v[116:119], v[136:139], v[222:225], v[116:119]
	v_mfma_f32_16x16x32_f16 v[84:87], v[140:143], v[222:225], v[84:87]
	v_mfma_f32_16x16x32_f16 v[52:55], v[144:147], v[222:225], v[52:55]
	v_mfma_f32_16x16x32_f16 v[20:23], v[148:151], v[222:225], v[20:23]
	global_load_lds_dwordx4 v130, s[4:5]
	s_add_u32 m0, s11, 0x3000
	s_waitcnt lgkmcnt(0)
	v_mfma_f32_16x16x32_f16 v[112:115], v[136:139], v[226:229], v[112:115]
	v_mfma_f32_16x16x32_f16 v[80:83], v[140:143], v[226:229], v[80:83]
	v_mfma_f32_16x16x32_f16 v[48:51], v[144:147], v[226:229], v[48:51]
	v_mfma_f32_16x16x32_f16 v[16:19], v[148:151], v[226:229], v[16:19]
	global_load_lds_dwordx4 v131, s[4:5]
	s_add_u32 s6, s6, 128
	s_addc_u32 s7, s7, 0
	s_add_u32 s4, s4, 128
	s_addc_u32 s5, s5, 0
	s_waitcnt vmcnt(8)
	s_barrier
	ds_read_b128 v[182:185], v176 offset:32768
	ds_read_b128 v[186:189], v176 offset:34816
	ds_read_b128 v[190:193], v176 offset:36864
	ds_read_b128 v[194:197], v176 offset:38912
	ds_read_b128 v[198:201], v178 offset:32768
	ds_read_b128 v[202:205], v178 offset:34816
	ds_read_b128 v[222:225], v178 offset:36864
	ds_read_b128 v[226:229], v178 offset:38912
	s_add_u32 m0, s11, 0x4000
	s_waitcnt lgkmcnt(7)
	v_mfma_f32_16x16x32_f16 v[108:111], v[230:233], v[182:185], v[108:111]
	v_mfma_f32_16x16x32_f16 v[76:79], v[234:237], v[182:185], v[76:79]
	v_mfma_f32_16x16x32_f16 v[44:47], v[238:241], v[182:185], v[44:47]
	v_mfma_f32_16x16x32_f16 v[12:15], v[242:245], v[182:185], v[12:15]
	global_load_lds_dwordx4 v128, s[18:19]
	s_add_u32 m0, s11, 0x5000
	s_waitcnt lgkmcnt(6)
	v_mfma_f32_16x16x32_f16 v[104:107], v[230:233], v[186:189], v[104:107]
	v_mfma_f32_16x16x32_f16 v[72:75], v[234:237], v[186:189], v[72:75]
	v_mfma_f32_16x16x32_f16 v[40:43], v[238:241], v[186:189], v[40:43]
	v_mfma_f32_16x16x32_f16 v[8:11], v[242:245], v[186:189], v[8:11]
	global_load_lds_dwordx4 v129, s[18:19]
	s_add_u32 m0, s11, 0x6000
	s_waitcnt lgkmcnt(5)
	v_mfma_f32_16x16x32_f16 v[100:103], v[230:233], v[190:193], v[100:103]
	v_mfma_f32_16x16x32_f16 v[68:71], v[234:237], v[190:193], v[68:71]
	v_mfma_f32_16x16x32_f16 v[36:39], v[238:241], v[190:193], v[36:39]
	v_mfma_f32_16x16x32_f16 v[4:7], v[242:245], v[190:193], v[4:7]
	global_load_lds_dwordx4 v132, s[18:19]
	s_add_u32 m0, s11, 0x7000
	s_waitcnt lgkmcnt(4)
	v_mfma_f32_16x16x32_f16 v[96:99], v[230:233], v[194:197], v[96:99]
	v_mfma_f32_16x16x32_f16 v[64:67], v[234:237], v[194:197], v[64:67]
	v_mfma_f32_16x16x32_f16 v[32:35], v[238:241], v[194:197], v[32:35]
	v_mfma_f32_16x16x32_f16 v[0:3], v[242:245], v[194:197], v[0:3]
	global_load_lds_dwordx4 v133, s[18:19]
	s_waitcnt lgkmcnt(3)
	v_mfma_f32_16x16x32_f16 v[108:111], v[136:139], v[198:201], v[108:111]
	v_mfma_f32_16x16x32_f16 v[76:79], v[140:143], v[198:201], v[76:79]
	v_mfma_f32_16x16x32_f16 v[44:47], v[144:147], v[198:201], v[44:47]
	v_mfma_f32_16x16x32_f16 v[12:15], v[148:151], v[198:201], v[12:15]
	s_waitcnt lgkmcnt(2)
	v_mfma_f32_16x16x32_f16 v[104:107], v[136:139], v[202:205], v[104:107]
	v_mfma_f32_16x16x32_f16 v[72:75], v[140:143], v[202:205], v[72:75]
	v_mfma_f32_16x16x32_f16 v[40:43], v[144:147], v[202:205], v[40:43]
	v_mfma_f32_16x16x32_f16 v[8:11], v[148:151], v[202:205], v[8:11]
	s_waitcnt lgkmcnt(1)
	v_mfma_f32_16x16x32_f16 v[100:103], v[136:139], v[222:225], v[100:103]
	v_mfma_f32_16x16x32_f16 v[68:71], v[140:143], v[222:225], v[68:71]
	v_mfma_f32_16x16x32_f16 v[36:39], v[144:147], v[222:225], v[36:39]
	v_mfma_f32_16x16x32_f16 v[4:7], v[148:151], v[222:225], v[4:7]
	s_waitcnt lgkmcnt(0)
	v_mfma_f32_16x16x32_f16 v[96:99], v[136:139], v[226:229], v[96:99]
	v_mfma_f32_16x16x32_f16 v[64:67], v[140:143], v[226:229], v[64:67]
	v_mfma_f32_16x16x32_f16 v[32:35], v[144:147], v[226:229], v[32:35]
	v_mfma_f32_16x16x32_f16 v[0:3], v[148:151], v[226:229], v[0:3]
	s_add_u32 s18, s18, 128
	s_addc_u32 s19, s19, 0
	s_waitcnt vmcnt(4)
	s_barrier
	ds_read_b128 v[230:233], v175 offset:0
	ds_read_b128 v[234:237], v175 offset:2048
	ds_read_b128 v[238:241], v175 offset:4096
	ds_read_b128 v[242:245], v175 offset:6144
	ds_read_b128 v[136:139], v177 offset:0
	ds_read_b128 v[140:143], v177 offset:2048
	ds_read_b128 v[144:147], v177 offset:4096
	ds_read_b128 v[148:151], v177 offset:6144
	ds_read_b128 v[182:185], v176 offset:49152
	ds_read_b128 v[186:189], v176 offset:51200
	ds_read_b128 v[190:193], v176 offset:53248
	ds_read_b128 v[194:197], v176 offset:55296
	s_waitcnt lgkmcnt(3)
	v_mfma_f32_16x16x32_f16 v[124:127], v[230:233], v[182:185], v[124:127]
	v_mfma_f32_16x16x32_f16 v[92:95], v[234:237], v[182:185], v[92:95]
	v_mfma_f32_16x16x32_f16 v[60:63], v[238:241], v[182:185], v[60:63]
	v_mfma_f32_16x16x32_f16 v[28:31], v[242:245], v[182:185], v[28:31]
	s_barrier
	ds_read_b128 v[198:201], v178 offset:49152
	ds_read_b128 v[202:205], v178 offset:51200
	ds_read_b128 v[222:225], v178 offset:53248
	ds_read_b128 v[226:229], v178 offset:55296
	s_waitcnt lgkmcnt(6)
	v_mfma_f32_16x16x32_f16 v[120:123], v[230:233], v[186:189], v[120:123]
	v_mfma_f32_16x16x32_f16 v[88:91], v[234:237], v[186:189], v[88:91]
	v_mfma_f32_16x16x32_f16 v[56:59], v[238:241], v[186:189], v[56:59]
	v_mfma_f32_16x16x32_f16 v[24:27], v[242:245], v[186:189], v[24:27]
	s_waitcnt lgkmcnt(5)
	v_mfma_f32_16x16x32_f16 v[116:119], v[230:233], v[190:193], v[116:119]
	v_mfma_f32_16x16x32_f16 v[84:87], v[234:237], v[190:193], v[84:87]
	v_mfma_f32_16x16x32_f16 v[52:55], v[238:241], v[190:193], v[52:55]
	v_mfma_f32_16x16x32_f16 v[20:23], v[242:245], v[190:193], v[20:23]
	s_waitcnt lgkmcnt(4)
	v_mfma_f32_16x16x32_f16 v[112:115], v[230:233], v[194:197], v[112:115]
	v_mfma_f32_16x16x32_f16 v[80:83], v[234:237], v[194:197], v[80:83]
	v_mfma_f32_16x16x32_f16 v[48:51], v[238:241], v[194:197], v[48:51]
	v_mfma_f32_16x16x32_f16 v[16:19], v[242:245], v[194:197], v[16:19]
	s_waitcnt lgkmcnt(3)
	v_mfma_f32_16x16x32_f16 v[124:127], v[136:139], v[198:201], v[124:127]
	v_mfma_f32_16x16x32_f16 v[92:95], v[140:143], v[198:201], v[92:95]
	v_mfma_f32_16x16x32_f16 v[60:63], v[144:147], v[198:201], v[60:63]
	v_mfma_f32_16x16x32_f16 v[28:31], v[148:151], v[198:201], v[28:31]
	s_waitcnt lgkmcnt(2)
	v_mfma_f32_16x16x32_f16 v[120:123], v[136:139], v[202:205], v[120:123]
	v_mfma_f32_16x16x32_f16 v[88:91], v[140:143], v[202:205], v[88:91]
	v_mfma_f32_16x16x32_f16 v[56:59], v[144:147], v[202:205], v[56:59]
	v_mfma_f32_16x16x32_f16 v[24:27], v[148:151], v[202:205], v[24:27]
	s_waitcnt lgkmcnt(1)
	v_mfma_f32_16x16x32_f16 v[116:119], v[136:139], v[222:225], v[116:119]
	v_mfma_f32_16x16x32_f16 v[84:87], v[140:143], v[222:225], v[84:87]
	v_mfma_f32_16x16x32_f16 v[52:55], v[144:147], v[222:225], v[52:55]
	v_mfma_f32_16x16x32_f16 v[20:23], v[148:151], v[222:225], v[20:23]
	s_waitcnt lgkmcnt(0)
	v_mfma_f32_16x16x32_f16 v[112:115], v[136:139], v[226:229], v[112:115]
	v_mfma_f32_16x16x32_f16 v[80:83], v[140:143], v[226:229], v[80:83]
	v_mfma_f32_16x16x32_f16 v[48:51], v[144:147], v[226:229], v[48:51]
	v_mfma_f32_16x16x32_f16 v[16:19], v[148:151], v[226:229], v[16:19]
	s_waitcnt vmcnt(0)
	s_barrier
	ds_read_b128 v[182:185], v176 offset:16384
	ds_read_b128 v[186:189], v176 offset:18432
	ds_read_b128 v[190:193], v176 offset:20480
	ds_read_b128 v[194:197], v176 offset:22528
	ds_read_b128 v[198:201], v178 offset:16384
	ds_read_b128 v[202:205], v178 offset:18432
	ds_read_b128 v[222:225], v178 offset:20480
	ds_read_b128 v[226:229], v178 offset:22528
	s_waitcnt lgkmcnt(7)
	v_mfma_f32_16x16x32_f16 v[108:111], v[230:233], v[182:185], v[108:111]
	v_mfma_f32_16x16x32_f16 v[76:79], v[234:237], v[182:185], v[76:79]
	v_mfma_f32_16x16x32_f16 v[44:47], v[238:241], v[182:185], v[44:47]
	v_mfma_f32_16x16x32_f16 v[12:15], v[242:245], v[182:185], v[12:15]
	s_waitcnt lgkmcnt(6)
	v_mfma_f32_16x16x32_f16 v[104:107], v[230:233], v[186:189], v[104:107]
	v_mfma_f32_16x16x32_f16 v[72:75], v[234:237], v[186:189], v[72:75]
	v_mfma_f32_16x16x32_f16 v[40:43], v[238:241], v[186:189], v[40:43]
	v_mfma_f32_16x16x32_f16 v[8:11], v[242:245], v[186:189], v[8:11]
	s_waitcnt lgkmcnt(5)
	v_mfma_f32_16x16x32_f16 v[100:103], v[230:233], v[190:193], v[100:103]
	v_mfma_f32_16x16x32_f16 v[68:71], v[234:237], v[190:193], v[68:71]
	v_mfma_f32_16x16x32_f16 v[36:39], v[238:241], v[190:193], v[36:39]
	v_mfma_f32_16x16x32_f16 v[4:7], v[242:245], v[190:193], v[4:7]
	s_waitcnt lgkmcnt(4)
	v_mfma_f32_16x16x32_f16 v[96:99], v[230:233], v[194:197], v[96:99]
	v_mfma_f32_16x16x32_f16 v[64:67], v[234:237], v[194:197], v[64:67]
	v_mfma_f32_16x16x32_f16 v[32:35], v[238:241], v[194:197], v[32:35]
	v_mfma_f32_16x16x32_f16 v[0:3], v[242:245], v[194:197], v[0:3]
	s_waitcnt lgkmcnt(3)
	v_mfma_f32_16x16x32_f16 v[108:111], v[136:139], v[198:201], v[108:111]
	v_mfma_f32_16x16x32_f16 v[76:79], v[140:143], v[198:201], v[76:79]
	v_mfma_f32_16x16x32_f16 v[44:47], v[144:147], v[198:201], v[44:47]
	v_mfma_f32_16x16x32_f16 v[12:15], v[148:151], v[198:201], v[12:15]
	s_waitcnt lgkmcnt(2)
	v_mfma_f32_16x16x32_f16 v[104:107], v[136:139], v[202:205], v[104:107]
	v_mfma_f32_16x16x32_f16 v[72:75], v[140:143], v[202:205], v[72:75]
	v_mfma_f32_16x16x32_f16 v[40:43], v[144:147], v[202:205], v[40:43]
	v_mfma_f32_16x16x32_f16 v[8:11], v[148:151], v[202:205], v[8:11]
	s_waitcnt lgkmcnt(1)
	v_mfma_f32_16x16x32_f16 v[100:103], v[136:139], v[222:225], v[100:103]
	v_mfma_f32_16x16x32_f16 v[68:71], v[140:143], v[222:225], v[68:71]
	v_mfma_f32_16x16x32_f16 v[36:39], v[144:147], v[222:225], v[36:39]
	v_mfma_f32_16x16x32_f16 v[4:7], v[148:151], v[222:225], v[4:7]
	s_waitcnt lgkmcnt(0)
	v_mfma_f32_16x16x32_f16 v[96:99], v[136:139], v[226:229], v[96:99]
	v_mfma_f32_16x16x32_f16 v[64:67], v[140:143], v[226:229], v[64:67]
	v_mfma_f32_16x16x32_f16 v[32:35], v[144:147], v[226:229], v[32:35]
	v_mfma_f32_16x16x32_f16 v[0:3], v[148:151], v[226:229], v[0:3]
	s_nop 7
	s_cmpk_lt_u32 s9, 0x620
	s_cselect_b64 s[44:45], -1, 0
	s_cmpk_gt_u32 s9, 0x61f
	s_cselect_b64 s[4:5], -1, 0
	s_cmp_lt_u32 s16, 6
	s_cselect_b64 s[6:7], -1, 0
	s_and_b64 s[4:5], s[4:5], s[6:7]
	s_and_b64 vcc, exec, s[4:5]
	s_cbranch_vccz .LBB0_320
	v_add_u32_e32 v128, s8, v174
	s_movk_i32 s4, 0x380
	v_and_or_b32 v128, v128, s4, v166
	v_readlane_b32 s4, v254, 41
	v_lshl_or_b32 v168, v128, 9, v180
	v_readlane_b32 s5, v254, 42
	s_nop 4
	global_load_dwordx4 v[130:133], v168, s[4:5] offset:16
	global_load_dwordx4 v[152:155], v168, s[4:5]
	v_lshl_add_u64 v[128:129], s[4:5], 0, v[168:169]
	s_waitcnt vmcnt(1)
	v_mul_f32_e32 v158, v62, v131
	s_waitcnt vmcnt(0)
	v_mov_b32_e32 v150, v153
	v_mov_b32_e32 v153, v154
	v_mul_f32_e32 v154, v126, v130
	v_mul_f32_e32 v160, v126, v131
	v_mul_f32_e32 v130, v62, v130
	v_mov_b32_e32 v62, v127
	v_mov_b32_e32 v126, v63
	v_mov_b32_e32 v151, v155
	v_pk_mul_f32 v[162:163], v[62:63], v[132:133]
	v_pk_mul_f32 v[62:63], v[126:127], v[132:133]
	v_pk_mul_f32 v[156:157], v[124:125], v[150:151]
	v_pk_mul_f32 v[150:151], v[60:61], v[150:151]
	v_mov_b32_e32 v155, v162
	v_mov_b32_e32 v159, v163
	v_mov_b32_e32 v131, v62
	v_mov_b32_e32 v161, v63
	v_pk_fma_f32 v[124:125], v[124:125], v[152:153], v[150:151] neg_lo:[0,0,1] neg_hi:[0,0,1]
	v_pk_add_f32 v[150:151], v[154:155], v[158:159] neg_lo:[0,1] neg_hi:[0,1]
	v_pk_fma_f32 v[60:61], v[60:61], v[152:153], v[156:157]
	v_pk_add_f32 v[62:63], v[130:131], v[160:161]
	global_load_dwordx4 v[130:133], v168, s[4:5] offset:144
	global_load_dwordx4 v[154:157], v168, s[4:5] offset:128
	s_mov_b64 s[4:5], 0x2080
	s_waitcnt vmcnt(1)
	v_mul_f32_e32 v152, v94, v130
	s_waitcnt vmcnt(0)
	v_mov_b32_e32 v126, v155
	v_mov_b32_e32 v127, v157
	v_pk_mul_f32 v[158:159], v[92:93], v[126:127]
	v_mov_b32_e32 v155, v156
	v_pk_mul_f32 v[126:127], v[28:29], v[126:127]
	v_mul_f32_e32 v156, v30, v131
	v_mul_f32_e32 v160, v94, v131
	v_mul_f32_e32 v130, v30, v130
	v_mov_b32_e32 v30, v95
	v_mov_b32_e32 v94, v31
	v_pk_mul_f32 v[162:163], v[30:31], v[132:133]
	v_pk_fma_f32 v[92:93], v[92:93], v[154:155], v[126:127] neg_lo:[0,0,1] neg_hi:[0,0,1]
	v_pk_mul_f32 v[30:31], v[94:95], v[132:133]
	v_add_co_u32_e32 v126, vcc, s33, v128
	v_mov_b32_e32 v153, v162
	v_mov_b32_e32 v157, v163
	v_mov_b32_e32 v131, v30
	v_mov_b32_e32 v161, v31
	v_addc_co_u32_e32 v127, vcc, 0, v129, vcc
	v_pk_add_f32 v[152:153], v[152:153], v[156:157] neg_lo:[0,1] neg_hi:[0,1]
	v_pk_fma_f32 v[28:29], v[28:29], v[154:155], v[158:159]
	v_pk_add_f32 v[30:31], v[130:131], v[160:161]
	v_lshl_add_u64 v[94:95], v[128:129], 0, s[26:27]
	global_load_dwordx4 v[130:133], v[126:127], off
	global_load_dwordx4 v[154:157], v[94:95], off offset:16
	s_waitcnt vmcnt(1)
	v_mov_b32_e32 v94, v131
	s_waitcnt vmcnt(0)
	v_mul_f32_e32 v160, v58, v155
	v_mul_f32_e32 v164, v58, v154
	v_mov_b32_e32 v58, v123
	v_mov_b32_e32 v95, v133
	v_mov_b32_e32 v131, v132
	v_mul_f32_e32 v132, v122, v154
	v_mul_f32_e32 v162, v122, v155
	v_pk_mul_f32 v[154:155], v[58:59], v[156:157]
	v_pk_mul_f32 v[158:159], v[120:121], v[94:95]
	v_pk_mul_f32 v[94:95], v[56:57], v[94:95]
	v_mov_b32_e32 v133, v154
	v_mov_b32_e32 v161, v155
	v_mov_b32_e32 v122, v59
	v_pk_fma_f32 v[120:121], v[120:121], v[130:131], v[94:95] neg_lo:[0,0,1] neg_hi:[0,0,1]
	v_pk_add_f32 v[154:155], v[132:133], v[160:161] neg_lo:[0,1] neg_hi:[0,1]
	v_pk_mul_f32 v[58:59], v[122:123], v[156:157]
	v_pk_fma_f32 v[56:57], v[56:57], v[130:131], v[158:159]
	v_lshl_add_u64 v[94:95], v[128:129], 0, s[4:5]
	global_load_dwordx4 v[130:133], v[126:127], off offset:128
	global_load_dwordx4 v[156:159], v[94:95], off offset:16
	v_mov_b32_e32 v165, v58
	v_mov_b32_e32 v163, v59
	v_pk_add_f32 v[58:59], v[164:165], v[162:163]
	s_mov_b64 s[4:5], 0x4080
	s_waitcnt vmcnt(1)
	v_mov_b32_e32 v94, v131
	v_mov_b32_e32 v131, v132
	s_waitcnt vmcnt(0)
	v_mul_f32_e32 v126, v90, v156
	v_mul_f32_e32 v132, v26, v157
	v_mul_f32_e32 v160, v90, v157
	v_mul_f32_e32 v156, v26, v156
	v_mov_b32_e32 v26, v91
	v_mov_b32_e32 v90, v27
	v_mov_b32_e32 v95, v133
	v_pk_mul_f32 v[162:163], v[26:27], v[158:159]
	v_pk_mul_f32 v[26:27], v[90:91], v[158:159]
	v_add_co_u32_e32 v90, vcc, s97, v128
	v_pk_mul_f32 v[122:123], v[88:89], v[94:95]
	v_pk_mul_f32 v[94:95], v[24:25], v[94:95]
	v_mov_b32_e32 v127, v162
	v_mov_b32_e32 v133, v163
	v_mov_b32_e32 v157, v26
	v_mov_b32_e32 v161, v27
	v_addc_co_u32_e32 v91, vcc, 0, v129, vcc
	v_pk_fma_f32 v[88:89], v[88:89], v[130:131], v[94:95] neg_lo:[0,0,1] neg_hi:[0,0,1]
	v_pk_add_f32 v[94:95], v[126:127], v[132:133] neg_lo:[0,1] neg_hi:[0,1]
	v_pk_fma_f32 v[24:25], v[24:25], v[130:131], v[122:123]
	v_pk_add_f32 v[26:27], v[156:157], v[160:161]
	v_lshl_add_u64 v[122:123], v[128:129], 0, s[84:85]
	global_load_dwordx4 v[130:133], v[90:91], off
	global_load_dwordx4 v[156:159], v[122:123], off offset:16
	s_waitcnt vmcnt(1)
	v_mov_b32_e32 v122, v131
	v_mov_b32_e32 v131, v132
	s_waitcnt vmcnt(0)
	v_mul_f32_e32 v132, v118, v156
	v_mul_f32_e32 v160, v54, v157
	v_mul_f32_e32 v162, v118, v157
	v_mul_f32_e32 v156, v54, v156
	v_mov_b32_e32 v54, v119
	v_mov_b32_e32 v118, v55
	v_mov_b32_e32 v123, v133
	v_pk_mul_f32 v[164:165], v[54:55], v[158:159]
	v_pk_mul_f32 v[54:55], v[118:119], v[158:159]
	v_pk_mul_f32 v[126:127], v[116:117], v[122:123]
	v_pk_mul_f32 v[122:123], v[52:53], v[122:123]
	v_mov_b32_e32 v133, v164
	v_mov_b32_e32 v161, v165
	v_mov_b32_e32 v157, v54
	v_mov_b32_e32 v163, v55
	v_pk_fma_f32 v[116:117], v[116:117], v[130:131], v[122:123] neg_lo:[0,0,1] neg_hi:[0,0,1]
	v_pk_add_f32 v[122:123], v[132:133], v[160:161] neg_lo:[0,1] neg_hi:[0,1]
	v_pk_fma_f32 v[52:53], v[52:53], v[130:131], v[126:127]
	v_pk_add_f32 v[54:55], v[156:157], v[162:163]
	v_lshl_add_u64 v[118:119], v[128:129], 0, s[4:5]
	global_load_dwordx4 v[130:133], v[90:91], off offset:128
	global_load_dwordx4 v[156:159], v[118:119], off offset:16
	s_mov_b64 s[4:5], 0x6080
	s_waitcnt vmcnt(1)
	v_mov_b32_e32 v90, v131
	v_mov_b32_e32 v131, v132
	s_waitcnt vmcnt(0)
	v_mul_f32_e32 v126, v86, v156
	v_mul_f32_e32 v132, v22, v157
	v_mul_f32_e32 v156, v22, v156
	v_mov_b32_e32 v22, v87
	v_mov_b32_e32 v91, v133
	v_pk_mul_f32 v[162:163], v[22:23], v[158:159]
	v_pk_mul_f32 v[118:119], v[84:85], v[90:91]
	v_pk_mul_f32 v[90:91], v[20:21], v[90:91]
	v_mul_f32_e32 v160, v86, v157
	v_mov_b32_e32 v127, v162
	v_mov_b32_e32 v133, v163
	v_mov_b32_e32 v86, v23
	v_pk_fma_f32 v[84:85], v[84:85], v[130:131], v[90:91] neg_lo:[0,0,1] neg_hi:[0,0,1]
	v_pk_add_f32 v[90:91], v[126:127], v[132:133] neg_lo:[0,1] neg_hi:[0,1]
	v_pk_mul_f32 v[22:23], v[86:87], v[158:159]
	v_add_co_u32_e32 v126, vcc, s24, v128
	v_mov_b32_e32 v157, v22
	v_mov_b32_e32 v161, v23
	v_addc_co_u32_e32 v127, vcc, 0, v129, vcc
	v_pk_fma_f32 v[20:21], v[20:21], v[130:131], v[118:119]
	v_pk_add_f32 v[22:23], v[156:157], v[160:161]
	v_lshl_add_u64 v[86:87], v[128:129], 0, s[28:29]
	global_load_dwordx4 v[130:133], v[126:127], off
	global_load_dwordx4 v[156:159], v[86:87], off offset:16
	s_waitcnt vmcnt(1)
	v_mov_b32_e32 v86, v131
	v_mov_b32_e32 v131, v132
	s_waitcnt vmcnt(0)
	v_mul_f32_e32 v118, v114, v156
	v_mul_f32_e32 v132, v50, v157
	v_mul_f32_e32 v162, v114, v157
	v_mul_f32_e32 v156, v50, v156
	v_mov_b32_e32 v50, v115
	v_mov_b32_e32 v114, v51
	v_mov_b32_e32 v87, v133
	v_pk_mul_f32 v[164:165], v[50:51], v[158:159]
	v_pk_mul_f32 v[50:51], v[114:115], v[158:159]
	v_pk_mul_f32 v[160:161], v[112:113], v[86:87]
	v_pk_mul_f32 v[86:87], v[48:49], v[86:87]
	v_mov_b32_e32 v119, v164
	v_mov_b32_e32 v133, v165
	v_mov_b32_e32 v157, v50
	v_mov_b32_e32 v163, v51
	v_pk_fma_f32 v[112:113], v[112:113], v[130:131], v[86:87] neg_lo:[0,0,1] neg_hi:[0,0,1]
	v_pk_add_f32 v[118:119], v[118:119], v[132:133] neg_lo:[0,1] neg_hi:[0,1]
	v_pk_fma_f32 v[48:49], v[48:49], v[130:131], v[160:161]
	v_pk_add_f32 v[50:51], v[156:157], v[162:163]
	v_lshl_add_u64 v[86:87], v[128:129], 0, s[4:5]
	global_load_dwordx4 v[130:133], v[126:127], off offset:128
	global_load_dwordx4 v[156:159], v[86:87], off offset:16
	s_mov_b64 s[4:5], 0x8000
	s_waitcnt vmcnt(1)
	v_mov_b32_e32 v86, v131
	v_mov_b32_e32 v131, v132
	s_waitcnt vmcnt(0)
	v_mul_f32_e32 v126, v82, v156
	v_mul_f32_e32 v132, v18, v157
	v_mul_f32_e32 v156, v18, v156
	v_mov_b32_e32 v18, v83
	v_mov_b32_e32 v87, v133
	v_mul_f32_e32 v160, v82, v157
	v_pk_mul_f32 v[162:163], v[18:19], v[158:159]
	v_mov_b32_e32 v82, v19
	v_pk_mul_f32 v[114:115], v[80:81], v[86:87]
	v_pk_mul_f32 v[86:87], v[16:17], v[86:87]
	v_mov_b32_e32 v127, v162
	v_mov_b32_e32 v133, v163
	v_pk_mul_f32 v[18:19], v[82:83], v[158:159]
	v_lshl_add_u64 v[82:83], v[128:129], 0, s[4:5]
	s_mov_b32 s4, 0x8000
	v_pk_fma_f32 v[80:81], v[80:81], v[130:131], v[86:87] neg_lo:[0,0,1] neg_hi:[0,0,1]
	v_pk_add_f32 v[86:87], v[126:127], v[132:133] neg_lo:[0,1] neg_hi:[0,1]
	v_add_co_u32_e32 v126, vcc, s4, v128
	v_mov_b32_e32 v157, v18
	v_mov_b32_e32 v161, v19
	v_addc_co_u32_e32 v127, vcc, 0, v129, vcc
	v_pk_fma_f32 v[16:17], v[16:17], v[130:131], v[114:115]
	v_pk_add_f32 v[18:19], v[156:157], v[160:161]
	global_load_dwordx4 v[130:133], v[126:127], off
	global_load_dwordx4 v[156:159], v[82:83], off offset:16
	s_mov_b64 s[4:5], 0x8080
	s_waitcnt vmcnt(1)
	v_mov_b32_e32 v82, v131
	v_mov_b32_e32 v131, v132
	s_waitcnt vmcnt(0)
	v_mul_f32_e32 v114, v110, v156
	v_mul_f32_e32 v132, v46, v157
	v_mul_f32_e32 v162, v110, v157
	v_mul_f32_e32 v156, v46, v156
	v_mov_b32_e32 v46, v111
	v_mov_b32_e32 v110, v47
	v_mov_b32_e32 v83, v133
	v_pk_mul_f32 v[164:165], v[46:47], v[158:159]
	v_pk_mul_f32 v[46:47], v[110:111], v[158:159]
	v_pk_mul_f32 v[160:161], v[108:109], v[82:83]
	v_pk_mul_f32 v[82:83], v[44:45], v[82:83]
	v_mov_b32_e32 v115, v164
	v_mov_b32_e32 v133, v165
	v_mov_b32_e32 v157, v46
	v_mov_b32_e32 v163, v47
	v_pk_fma_f32 v[108:109], v[108:109], v[130:131], v[82:83] neg_lo:[0,0,1] neg_hi:[0,0,1]
	v_pk_add_f32 v[114:115], v[114:115], v[132:133] neg_lo:[0,1] neg_hi:[0,1]
	v_pk_fma_f32 v[44:45], v[44:45], v[130:131], v[160:161]
	v_pk_add_f32 v[46:47], v[156:157], v[162:163]
	v_lshl_add_u64 v[82:83], v[128:129], 0, s[4:5]
	global_load_dwordx4 v[130:133], v[126:127], off offset:128
	global_load_dwordx4 v[156:159], v[82:83], off offset:16
	s_mov_b64 s[4:5], 0xa000
	s_waitcnt vmcnt(1)
	v_mov_b32_e32 v82, v131
	v_mov_b32_e32 v131, v132
	s_waitcnt vmcnt(0)
	v_mul_f32_e32 v126, v78, v156
	v_mul_f32_e32 v132, v14, v157
	v_mul_f32_e32 v156, v14, v156
	v_mov_b32_e32 v14, v79
	v_mov_b32_e32 v83, v133
	v_mul_f32_e32 v160, v78, v157
	v_pk_mul_f32 v[162:163], v[14:15], v[158:159]
	v_mov_b32_e32 v78, v15
	v_pk_mul_f32 v[110:111], v[76:77], v[82:83]
	v_pk_mul_f32 v[82:83], v[12:13], v[82:83]
	v_mov_b32_e32 v127, v162
	v_mov_b32_e32 v133, v163
	v_pk_mul_f32 v[14:15], v[78:79], v[158:159]
	v_lshl_add_u64 v[78:79], v[128:129], 0, s[4:5]
	s_mov_b32 s4, 0xa000
	v_pk_fma_f32 v[76:77], v[76:77], v[130:131], v[82:83] neg_lo:[0,0,1] neg_hi:[0,0,1]
	v_pk_add_f32 v[82:83], v[126:127], v[132:133] neg_lo:[0,1] neg_hi:[0,1]
	v_add_co_u32_e32 v126, vcc, s4, v128
	v_mov_b32_e32 v157, v14
	v_mov_b32_e32 v161, v15
	v_addc_co_u32_e32 v127, vcc, 0, v129, vcc
	v_pk_fma_f32 v[12:13], v[12:13], v[130:131], v[110:111]
	v_pk_add_f32 v[14:15], v[156:157], v[160:161]
	global_load_dwordx4 v[130:133], v[126:127], off
	global_load_dwordx4 v[156:159], v[78:79], off offset:16
	s_mov_b64 s[4:5], 0xa080
	s_waitcnt vmcnt(1)
	v_mov_b32_e32 v78, v131
	v_mov_b32_e32 v131, v132
	s_waitcnt vmcnt(0)
	v_mul_f32_e32 v110, v106, v156
	v_mul_f32_e32 v132, v42, v157
	v_mul_f32_e32 v162, v106, v157
	v_mul_f32_e32 v156, v42, v156
	v_mov_b32_e32 v42, v107
	v_mov_b32_e32 v106, v43
	v_mov_b32_e32 v79, v133
	v_pk_mul_f32 v[164:165], v[42:43], v[158:159]
	v_pk_mul_f32 v[42:43], v[106:107], v[158:159]
	v_pk_mul_f32 v[160:161], v[104:105], v[78:79]
	v_pk_mul_f32 v[78:79], v[40:41], v[78:79]
	v_mov_b32_e32 v111, v164
	v_mov_b32_e32 v133, v165
	v_mov_b32_e32 v157, v42
	v_mov_b32_e32 v163, v43
	v_pk_fma_f32 v[104:105], v[104:105], v[130:131], v[78:79] neg_lo:[0,0,1] neg_hi:[0,0,1]
	v_pk_add_f32 v[110:111], v[110:111], v[132:133] neg_lo:[0,1] neg_hi:[0,1]
	v_pk_fma_f32 v[40:41], v[40:41], v[130:131], v[160:161]
	v_pk_add_f32 v[42:43], v[156:157], v[162:163]
	v_lshl_add_u64 v[78:79], v[128:129], 0, s[4:5]
	global_load_dwordx4 v[130:133], v[126:127], off offset:128
	global_load_dwordx4 v[156:159], v[78:79], off offset:16
	s_mov_b64 s[4:5], 0xc000
	s_waitcnt vmcnt(1)
	v_mov_b32_e32 v78, v131
	v_mov_b32_e32 v131, v132
	s_waitcnt vmcnt(0)
	v_mul_f32_e32 v126, v74, v156
	v_mul_f32_e32 v132, v10, v157
	v_mul_f32_e32 v156, v10, v156
	v_mov_b32_e32 v10, v75
	v_mov_b32_e32 v79, v133
	v_mul_f32_e32 v160, v74, v157
	v_pk_mul_f32 v[162:163], v[10:11], v[158:159]
	v_mov_b32_e32 v74, v11
	v_pk_mul_f32 v[106:107], v[72:73], v[78:79]
	v_pk_mul_f32 v[78:79], v[8:9], v[78:79]
	v_mov_b32_e32 v127, v162
	v_mov_b32_e32 v133, v163
	v_pk_mul_f32 v[10:11], v[74:75], v[158:159]
	v_lshl_add_u64 v[74:75], v[128:129], 0, s[4:5]
	s_mov_b32 s4, 0xc000
	v_pk_fma_f32 v[72:73], v[72:73], v[130:131], v[78:79] neg_lo:[0,0,1] neg_hi:[0,0,1]
	v_pk_add_f32 v[78:79], v[126:127], v[132:133] neg_lo:[0,1] neg_hi:[0,1]
	v_add_co_u32_e32 v126, vcc, s4, v128
	v_mov_b32_e32 v157, v10
	v_mov_b32_e32 v161, v11
	v_addc_co_u32_e32 v127, vcc, 0, v129, vcc
	v_pk_fma_f32 v[8:9], v[8:9], v[130:131], v[106:107]
	v_pk_add_f32 v[10:11], v[156:157], v[160:161]
	global_load_dwordx4 v[130:133], v[126:127], off
	global_load_dwordx4 v[156:159], v[74:75], off offset:16
	s_mov_b64 s[4:5], 0xc080
	s_waitcnt vmcnt(1)
	v_mov_b32_e32 v74, v131
	v_mov_b32_e32 v131, v132
	s_waitcnt vmcnt(0)
	v_mul_f32_e32 v106, v102, v156
	v_mul_f32_e32 v132, v38, v157
	v_mul_f32_e32 v162, v102, v157
	v_mul_f32_e32 v156, v38, v156
	v_mov_b32_e32 v38, v103
	v_mov_b32_e32 v102, v39
	v_mov_b32_e32 v75, v133
	v_pk_mul_f32 v[164:165], v[38:39], v[158:159]
	v_pk_mul_f32 v[38:39], v[102:103], v[158:159]
	v_pk_mul_f32 v[160:161], v[100:101], v[74:75]
	v_pk_mul_f32 v[74:75], v[36:37], v[74:75]
	v_mov_b32_e32 v107, v164
	v_mov_b32_e32 v133, v165
	v_mov_b32_e32 v157, v38
	v_mov_b32_e32 v163, v39
	v_pk_fma_f32 v[100:101], v[100:101], v[130:131], v[74:75] neg_lo:[0,0,1] neg_hi:[0,0,1]
	v_pk_add_f32 v[106:107], v[106:107], v[132:133] neg_lo:[0,1] neg_hi:[0,1]
	v_pk_fma_f32 v[36:37], v[36:37], v[130:131], v[160:161]
	v_pk_add_f32 v[38:39], v[156:157], v[162:163]
	v_lshl_add_u64 v[74:75], v[128:129], 0, s[4:5]
	global_load_dwordx4 v[130:133], v[126:127], off offset:128
	global_load_dwordx4 v[156:159], v[74:75], off offset:16
	s_mov_b64 s[4:5], 0xe000
	s_waitcnt vmcnt(1)
	v_mov_b32_e32 v74, v131
	v_mov_b32_e32 v131, v132
	s_waitcnt vmcnt(0)
	v_mul_f32_e32 v126, v70, v156
	v_mul_f32_e32 v132, v6, v157
	v_mul_f32_e32 v156, v6, v156
	v_mov_b32_e32 v6, v71
	v_mov_b32_e32 v75, v133
	v_mul_f32_e32 v160, v70, v157
	v_pk_mul_f32 v[162:163], v[6:7], v[158:159]
	v_mov_b32_e32 v70, v7
	v_pk_mul_f32 v[102:103], v[68:69], v[74:75]
	v_pk_mul_f32 v[74:75], v[4:5], v[74:75]
	v_mov_b32_e32 v127, v162
	v_mov_b32_e32 v133, v163
	v_pk_mul_f32 v[6:7], v[70:71], v[158:159]
	v_lshl_add_u64 v[70:71], v[128:129], 0, s[4:5]
	s_mov_b32 s4, 0xe000
	v_pk_fma_f32 v[68:69], v[68:69], v[130:131], v[74:75] neg_lo:[0,0,1] neg_hi:[0,0,1]
	v_pk_add_f32 v[74:75], v[126:127], v[132:133] neg_lo:[0,1] neg_hi:[0,1]
	v_add_co_u32_e32 v126, vcc, s4, v128
	v_mov_b32_e32 v157, v6
	v_mov_b32_e32 v161, v7
	v_addc_co_u32_e32 v127, vcc, 0, v129, vcc
	v_pk_fma_f32 v[4:5], v[4:5], v[130:131], v[102:103]
	v_pk_add_f32 v[6:7], v[156:157], v[160:161]
	global_load_dwordx4 v[130:133], v[126:127], off
	global_load_dwordx4 v[156:159], v[70:71], off offset:16
	s_mov_b64 s[4:5], 0xe080
	s_waitcnt vmcnt(1)
	v_mov_b32_e32 v70, v131
	v_mov_b32_e32 v131, v132
	s_waitcnt vmcnt(0)
	v_mul_f32_e32 v102, v98, v156
	v_mul_f32_e32 v132, v34, v157
	v_mul_f32_e32 v156, v34, v156
	v_mov_b32_e32 v34, v99
	v_mov_b32_e32 v71, v133
	v_pk_mul_f32 v[164:165], v[34:35], v[158:159]
	v_pk_mul_f32 v[160:161], v[96:97], v[70:71]
	v_pk_mul_f32 v[70:71], v[32:33], v[70:71]
	v_mov_b32_e32 v103, v164
	v_mov_b32_e32 v133, v165
	v_pk_fma_f32 v[96:97], v[96:97], v[130:131], v[70:71] neg_lo:[0,0,1] neg_hi:[0,0,1]
	v_pk_add_f32 v[102:103], v[102:103], v[132:133] neg_lo:[0,1] neg_hi:[0,1]
	v_pk_fma_f32 v[32:33], v[32:33], v[130:131], v[160:161]
	v_lshl_add_u64 v[70:71], v[128:129], 0, s[4:5]
	global_load_dwordx4 v[126:129], v[126:127], off offset:128
	s_nop 0
	global_load_dwordx4 v[130:133], v[70:71], off offset:16
	v_mul_f32_e32 v162, v98, v157
	v_mov_b32_e32 v98, v35
	v_pk_mul_f32 v[34:35], v[98:99], v[158:159]
	s_waitcnt vmcnt(1)
	v_mov_b32_e32 v70, v127
	v_mov_b32_e32 v157, v34
	v_mov_b32_e32 v163, v35
	v_pk_add_f32 v[34:35], v[156:157], v[162:163]
	v_mov_b32_e32 v127, v128
	s_waitcnt vmcnt(0)
	v_mul_f32_e32 v128, v66, v130
	v_mul_f32_e32 v156, v2, v131
	v_mul_f32_e32 v130, v2, v130
	v_mov_b32_e32 v2, v67
	v_mov_b32_e32 v71, v129
	v_mul_f32_e32 v158, v66, v131
	v_pk_mul_f32 v[160:161], v[2:3], v[132:133]
	v_mov_b32_e32 v66, v3
	v_pk_mul_f32 v[98:99], v[64:65], v[70:71]
	v_pk_mul_f32 v[70:71], v[0:1], v[70:71]
	v_mov_b32_e32 v129, v160
	v_mov_b32_e32 v157, v161
	v_pk_mul_f32 v[2:3], v[66:67], v[132:133]
	v_pk_fma_f32 v[64:65], v[64:65], v[126:127], v[70:71] neg_lo:[0,0,1] neg_hi:[0,0,1]
	v_pk_add_f32 v[70:71], v[128:129], v[156:157] neg_lo:[0,1] neg_hi:[0,1]
	v_mov_b32_e32 v131, v2
	v_mov_b32_e32 v159, v3
	v_pk_fma_f32 v[0:1], v[0:1], v[126:127], v[98:99]
	v_pk_add_f32 v[2:3], v[130:131], v[158:159]
	v_mov_b32_e32 v66, v70
	v_mov_b32_e32 v67, v71
	v_mov_b32_e32 v70, v74
	v_mov_b32_e32 v71, v75
	v_mov_b32_e32 v74, v78
	v_mov_b32_e32 v75, v79
	v_mov_b32_e32 v78, v82
	v_mov_b32_e32 v79, v83
	v_mov_b32_e32 v82, v86
	v_mov_b32_e32 v83, v87
	v_mov_b32_e32 v86, v90
	v_mov_b32_e32 v87, v91
	v_mov_b32_e32 v90, v94
	v_mov_b32_e32 v91, v95
	v_mov_b32_e32 v94, v152
	v_mov_b32_e32 v95, v153
	v_mov_b32_e32 v98, v102
	v_mov_b32_e32 v99, v103
	v_mov_b32_e32 v102, v106
	v_mov_b32_e32 v103, v107
	v_mov_b32_e32 v106, v110
	v_mov_b32_e32 v107, v111
	v_mov_b32_e32 v110, v114
	v_mov_b32_e32 v111, v115
	v_mov_b32_e32 v114, v118
	v_mov_b32_e32 v115, v119
	v_mov_b32_e32 v118, v122
	v_mov_b32_e32 v119, v123
	v_mov_b32_e32 v122, v154
	v_mov_b32_e32 v123, v155
	v_mov_b32_e32 v126, v150
	v_mov_b32_e32 v127, v151

.LBB0_1352:
	s_lshr_b32 s4, s0, 4
	s_and_b32 s4, s4, 0x78
	s_and_b32 s5, s0, 7
	s_lshl_b32 s0, s0, 4
	s_or_b32 s4, s4, s5
	s_and_b32 s7, s0, 0x780
	s_lshl_b32 s4, s4, 7
	v_readfirstlane_b32 s8, v128
	v_readfirstlane_b32 s9, v129
	v_readfirstlane_b32 s10, v130
	v_readfirstlane_b32 s11, v131
	v_lshrrev_b32_e32 v198, 6, v171
	v_and_b32_e32 v199, 63, v171
	v_readfirstlane_b32 s12, v198
	s_lshl_b32 s16, s7, 12
	s_add_u32 s8, s8, s16
	s_addc_u32 s9, s9, 0
	s_lshl_b32 s16, s4, 12
	s_add_u32 s10, s10, s16
	s_addc_u32 s11, s11, 0
	s_add_u32 s14, s10, 0x20000
	s_addc_u32 s15, s11, 0
	v_lshrrev_b32_e32 v194, 4, v199
	v_and_b32_e32 v190, 7, v199
	v_lshrrev_b32_e32 v191, 3, v199
	s_and_b32 s16, s12, 1
	s_lshl_b32 s16, s16, 2
	v_or_b32_e32 v196, s16, v194
	v_xor_b32_e32 v190, v190, v196
	v_lshlrev_b32_e32 v190, 4, v190
	v_lshl_or_b32 v190, v191, 12, v190
	s_lshl_b32 s16, s12, 15
	v_add_u32_e32 v190, s16, v190
	v_add_u32_e32 v191, 0x20000, v190
	v_add_u32_e32 v192, 0x40000, v190
	v_add_u32_e32 v193, 0x60000, v190
	v_and_b32_e32 v198, 15, v199
	v_bfe_u32 v196, v198, 1, 3
	v_xor_b32_e32 v196, v196, v194
	v_lshlrev_b32_e32 v196, 4, v196
	v_lshl_or_b32 v196, v198, 7, v196
	s_and_b32 s16, s12, 1
	s_lshl_b32 s16, s16, 13
	v_add_u32_e32 v194, s16, v196
	s_lshr_b32 s17, s12, 1
	s_lshl_b32 s17, s17, 12
	s_add_u32 s17, s17, 0x8000
	v_add_u32_e32 v196, s17, v196
	v_xor_b32_e32 v195, 64, v194
	v_xor_b32_e32 v197, 64, v196
	s_lshl_b32 s12, s12, 10
	s_barrier
	s_lshl_b32 s16, s4, 13
	s_lshl_b32 s17, s7, 2
	s_add_u32 s16, s16, s17
	s_add_u32 s18, s94, s16
	s_addc_u32 s19, s95, 0
	v_readlane_b32 s36, v253, 0
	v_readlane_b32 s37, v253, 1
	v_readlane_b32 s40, v253, 2
	v_readlane_b32 s41, v253, 3
	s_cmpk_lt_u32 s4, 0x2000
	s_cselect_b32 s36, s36, s40
	s_cselect_b32 s37, s37, s41
	s_cselect_b32 s40, 0, 0x4000000
	s_sub_u32 s41, s16, s40
	s_add_u32 s36, s36, s41
	s_addc_u32 s37, s37, 0
	s_cmp_lg_u32 s46, 0
	s_cselect_b32 s36, s18, s36
	s_cselect_b32 s37, s19, s37
	s_sub_u32 s40, s4, 0x2000
	s_lshr_b32 s40, s40, 10
	s_add_u32 s40, s40, 1
	s_cmpk_lt_u32 s4, 0x2000
	s_cselect_b32 s40, 0, s40
	s_add_u32 s40, s40, s48
	s_mul_i32 s40, s40, 0x6000
	s_add_u32 s40, s40, 0x4000
	s_add_u32 s40, s40, s17
	v_readlane_b32 s38, v254, 45
	v_readlane_b32 s39, v254, 46
	s_add_u32 s38, s38, s40
	s_addc_u32 s39, s39, 0
	v_and_b32_e32 v150, 15, v199
	v_lshrrev_b32_e32 v148, 4, v199
	s_lshr_b32 s40, s12, 11
	s_lshl_b32 s40, s40, 6
	v_add_u32_e32 v150, s40, v150
	s_bfe_u32 s41, s12, 0x1000a
	s_lshl_b32 s41, s41, 6
	v_lshl_add_u32 v148, v148, 2, s41
	v_lshlrev_b32_e32 v148, 2, v148
	v_lshl_add_u32 v150, v150, 13, v148
	v_add_u32_e32 v151, 0x20000, v150
	v_add_u32_e32 v152, 0x40000, v150
	v_add_u32_e32 v153, 0x60000, v150
	global_load_dwordx4 v[60:63], v148, s[38:39] offset:0
	global_load_dwordx4 v[64:67], v148, s[38:39] offset:64
	global_load_dwordx4 v[68:71], v148, s[38:39] offset:128
	global_load_dwordx4 v[72:75], v148, s[38:39] offset:192
	global_load_dwordx4 v[76:79], v150, s[36:37] offset:0
	global_load_dwordx4 v[80:83], v150, s[36:37] offset:64
	global_load_dwordx4 v[84:87], v150, s[36:37] offset:128
	global_load_dwordx4 v[200:203], v150, s[36:37] offset:192
	global_load_dwordx4 v[204:207], v151, s[36:37] offset:0
	global_load_dwordx4 v[210:213], v151, s[36:37] offset:64
	global_load_dwordx4 v[222:225], v151, s[36:37] offset:128
	global_load_dwordx4 v[226:229], v151, s[36:37] offset:192
	global_load_dwordx4 v[230:233], v152, s[36:37] offset:0
	global_load_dwordx4 v[234:237], v152, s[36:37] offset:64
	global_load_dwordx4 v[238:241], v152, s[36:37] offset:128
	global_load_dwordx4 v[242:245], v152, s[36:37] offset:192
	global_load_dwordx4 v[246:249], v153, s[36:37] offset:0
	global_load_dwordx4 v[158:161], v153, s[36:37] offset:64
	global_load_dwordx4 v[162:165], v153, s[36:37] offset:128
	global_load_dwordx4 v[154:157], v153, s[36:37] offset:192
	s_add_u32 m0, s12, 0x8000
	s_nop 0
	global_load_lds_dwordx4 v190, s[10:11]
	s_add_u32 m0, s12, 0x9000
	s_nop 0
	global_load_lds_dwordx4 v192, s[10:11]
	s_add_u32 s10, s10, 128
	s_addc_u32 s11, s11, 0
	s_add_u32 m0, s12, 0xa000
	s_nop 0
	global_load_lds_dwordx4 v190, s[14:15]
	s_add_u32 m0, s12, 0xb000
	s_nop 0
	global_load_lds_dwordx4 v192, s[14:15]
	s_add_u32 s14, s14, 128
	s_addc_u32 s15, s15, 0
	s_add_u32 m0, s12, 0x0
	s_nop 0
	global_load_lds_dwordx4 v190, s[8:9]
	s_add_u32 m0, s12, 0x1000
	s_nop 0
	global_load_lds_dwordx4 v191, s[8:9]
	s_add_u32 m0, s12, 0x2000
	s_nop 0
	global_load_lds_dwordx4 v192, s[8:9]
	s_add_u32 m0, s12, 0x3000
	s_nop 0
	global_load_lds_dwordx4 v193, s[8:9]
	s_add_u32 s8, s8, 128
	s_addc_u32 s9, s9, 0
	s_add_u32 m0, s12, 0xc000
	s_nop 0
	global_load_lds_dwordx4 v190, s[10:11]
	s_add_u32 m0, s12, 0xd000
	s_nop 0
	global_load_lds_dwordx4 v192, s[10:11]
	s_add_u32 s10, s10, 128
	s_addc_u32 s11, s11, 0
	s_add_u32 m0, s12, 0xe000
	s_nop 0
	global_load_lds_dwordx4 v190, s[14:15]
	s_add_u32 m0, s12, 0xf000
	s_nop 0
	global_load_lds_dwordx4 v192, s[14:15]
	s_add_u32 s14, s14, 128
	s_addc_u32 s15, s15, 0
	s_add_u32 m0, s12, 0x4000
	s_nop 0
	global_load_lds_dwordx4 v190, s[8:9]
	s_add_u32 m0, s12, 0x5000
	s_nop 0
	global_load_lds_dwordx4 v191, s[8:9]
	s_add_u32 m0, s12, 0x6000
	s_nop 0
	global_load_lds_dwordx4 v192, s[8:9]
	s_add_u32 m0, s12, 0x7000
	s_nop 0
	global_load_lds_dwordx4 v193, s[8:9]
	s_add_u32 s8, s8, 128
	s_addc_u32 s9, s9, 0
	v_mov_b32_e32 v0, 0
	v_mov_b32_e32 v1, v0
	v_mov_b32_e32 v2, v0
	v_mov_b32_e32 v3, v0
	v_mov_b32_e32 v4, v0
	v_mov_b32_e32 v5, v0
	v_mov_b32_e32 v6, v0
	v_mov_b32_e32 v7, v0
	v_mov_b32_e32 v8, v0
	v_mov_b32_e32 v9, v0
	v_mov_b32_e32 v10, v0
	v_mov_b32_e32 v11, v0
	v_mov_b32_e32 v12, v0
	v_mov_b32_e32 v13, v0
	v_mov_b32_e32 v14, v0
	v_mov_b32_e32 v15, v0
	v_mov_b32_e32 v16, v0
	v_mov_b32_e32 v17, v0
	v_mov_b32_e32 v18, v0
	v_mov_b32_e32 v19, v0
	v_mov_b32_e32 v20, v0
	v_mov_b32_e32 v21, v0
	v_mov_b32_e32 v22, v0
	v_mov_b32_e32 v23, v0
	v_mov_b32_e32 v24, v0
	v_mov_b32_e32 v25, v0
	v_mov_b32_e32 v26, v0
	v_mov_b32_e32 v27, v0
	v_mov_b32_e32 v28, v0
	v_mov_b32_e32 v29, v0
	v_mov_b32_e32 v30, v0
	v_mov_b32_e32 v31, v0
	v_mov_b32_e32 v32, v0
	v_mov_b32_e32 v33, v0
	v_mov_b32_e32 v34, v0
	v_mov_b32_e32 v35, v0
	v_mov_b32_e32 v36, v0
	v_mov_b32_e32 v37, v0
	v_mov_b32_e32 v38, v0
	v_mov_b32_e32 v39, v0
	v_mov_b32_e32 v40, v0
	v_mov_b32_e32 v41, v0
	v_mov_b32_e32 v42, v0
	v_mov_b32_e32 v43, v0
	v_mov_b32_e32 v44, v0
	v_mov_b32_e32 v45, v0
	v_mov_b32_e32 v46, v0
	v_mov_b32_e32 v47, v0
	v_mov_b32_e32 v48, v0
	v_mov_b32_e32 v49, v0
	v_mov_b32_e32 v50, v0
	v_mov_b32_e32 v51, v0
	v_mov_b32_e32 v52, v0
	v_mov_b32_e32 v53, v0
	v_mov_b32_e32 v54, v0
	v_mov_b32_e32 v55, v0
	v_mov_b32_e32 v56, v0
	v_mov_b32_e32 v57, v0
	v_mov_b32_e32 v58, v0
	v_mov_b32_e32 v59, v0
	v_mov_b32_e32 v124, v0
	v_mov_b32_e32 v125, v0
	v_mov_b32_e32 v126, v0
	v_mov_b32_e32 v127, v0
	s_mov_b32 s13, 0
.Lgout_loop:
	s_waitcnt vmcnt(8)
	s_barrier
	ds_read_b128 v[90:93], v194 offset:0
	ds_read_b128 v[94:97], v194 offset:2048
	ds_read_b128 v[98:101], v194 offset:4096
	ds_read_b128 v[102:105], v194 offset:6144
	ds_read_b128 v[132:135], v196 offset:0
	ds_read_b128 v[136:139], v196 offset:2048
	ds_read_b128 v[106:109], v195 offset:0
	ds_read_b128 v[110:113], v195 offset:2048
	ds_read_b128 v[114:117], v195 offset:4096
	ds_read_b128 v[118:121], v195 offset:6144
	ds_read_b128 v[140:143], v197 offset:0
	ds_read_b128 v[144:147], v197 offset:2048
	s_waitcnt lgkmcnt(7)
	s_add_u32 m0, s12, 0x10000
	v_mfma_f32_16x16x32_f16 v[124:127], v[90:93], v[132:135], v[124:127]
	global_load_lds_dwordx4 v190, s[10:11]
	v_mfma_f32_16x16x32_f16 v[44:47], v[94:97], v[132:135], v[44:47]
	v_mfma_f32_16x16x32_f16 v[28:31], v[98:101], v[132:135], v[28:31]
	v_mfma_f32_16x16x32_f16 v[12:15], v[102:105], v[132:135], v[12:15]
	s_waitcnt lgkmcnt(6)
	s_add_u32 m0, s12, 0x11000
	v_mfma_f32_16x16x32_f16 v[56:59], v[90:93], v[136:139], v[56:59]
	global_load_lds_dwordx4 v192, s[10:11]
	v_mfma_f32_16x16x32_f16 v[40:43], v[94:97], v[136:139], v[40:43]
	v_mfma_f32_16x16x32_f16 v[24:27], v[98:101], v[136:139], v[24:27]
	v_mfma_f32_16x16x32_f16 v[8:11], v[102:105], v[136:139], v[8:11]
	s_waitcnt lgkmcnt(1)
	v_mfma_f32_16x16x32_f16 v[124:127], v[106:109], v[140:143], v[124:127]
	v_mfma_f32_16x16x32_f16 v[44:47], v[110:113], v[140:143], v[44:47]
	v_mfma_f32_16x16x32_f16 v[28:31], v[114:117], v[140:143], v[28:31]
	v_mfma_f32_16x16x32_f16 v[12:15], v[118:121], v[140:143], v[12:15]
	s_waitcnt lgkmcnt(0)
	v_mfma_f32_16x16x32_f16 v[56:59], v[106:109], v[144:147], v[56:59]
	v_mfma_f32_16x16x32_f16 v[40:43], v[110:113], v[144:147], v[40:43]
	v_mfma_f32_16x16x32_f16 v[24:27], v[114:117], v[144:147], v[24:27]
	v_mfma_f32_16x16x32_f16 v[8:11], v[118:121], v[144:147], v[8:11]
	s_add_u32 s10, s10, 128
	s_addc_u32 s11, s11, 0
	s_barrier
	ds_read_b128 v[174:177], v196 offset:8192
	ds_read_b128 v[178:181], v196 offset:10240
	ds_read_b128 v[182:185], v197 offset:8192
	ds_read_b128 v[186:189], v197 offset:10240
	s_waitcnt lgkmcnt(3)
	s_add_u32 m0, s12, 0x8000
	v_mfma_f32_16x16x32_f16 v[52:55], v[90:93], v[174:177], v[52:55]
	global_load_lds_dwordx4 v190, s[14:15]
	v_mfma_f32_16x16x32_f16 v[36:39], v[94:97], v[174:177], v[36:39]
	s_add_u32 m0, s12, 0x9000
	v_mfma_f32_16x16x32_f16 v[20:23], v[98:101], v[174:177], v[20:23]
	global_load_lds_dwordx4 v192, s[14:15]
	v_mfma_f32_16x16x32_f16 v[4:7], v[102:105], v[174:177], v[4:7]
	s_waitcnt lgkmcnt(2)
	s_add_u32 m0, s12, 0x0
	v_mfma_f32_16x16x32_f16 v[48:51], v[90:93], v[178:181], v[48:51]
	global_load_lds_dwordx4 v190, s[8:9]
	v_mfma_f32_16x16x32_f16 v[32:35], v[94:97], v[178:181], v[32:35]
	s_add_u32 m0, s12, 0x1000
	v_mfma_f32_16x16x32_f16 v[16:19], v[98:101], v[178:181], v[16:19]
	global_load_lds_dwordx4 v191, s[8:9]
	v_mfma_f32_16x16x32_f16 v[0:3], v[102:105], v[178:181], v[0:3]
	s_waitcnt lgkmcnt(1)
	s_add_u32 m0, s12, 0x2000
	v_mfma_f32_16x16x32_f16 v[52:55], v[106:109], v[182:185], v[52:55]
	global_load_lds_dwordx4 v192, s[8:9]
	v_mfma_f32_16x16x32_f16 v[36:39], v[110:113], v[182:185], v[36:39]
	v_mfma_f32_16x16x32_f16 v[20:23], v[114:117], v[182:185], v[20:23]
	v_mfma_f32_16x16x32_f16 v[4:7], v[118:121], v[182:185], v[4:7]
	s_waitcnt lgkmcnt(0)
	s_add_u32 m0, s12, 0x3000
	v_mfma_f32_16x16x32_f16 v[48:51], v[106:109], v[186:189], v[48:51]
	global_load_lds_dwordx4 v193, s[8:9]
	v_mfma_f32_16x16x32_f16 v[32:35], v[110:113], v[186:189], v[32:35]
	v_mfma_f32_16x16x32_f16 v[16:19], v[114:117], v[186:189], v[16:19]
	v_mfma_f32_16x16x32_f16 v[0:3], v[118:121], v[186:189], v[0:3]
	s_add_u32 s14, s14, 128
	s_addc_u32 s15, s15, 0
	s_add_u32 s8, s8, 128
	s_addc_u32 s9, s9, 0
	s_waitcnt vmcnt(8)
	s_barrier
	ds_read_b128 v[90:93], v194 offset:16384
	ds_read_b128 v[94:97], v194 offset:18432
	ds_read_b128 v[98:101], v194 offset:20480
	ds_read_b128 v[102:105], v194 offset:22528
	ds_read_b128 v[132:135], v196 offset:16384
	ds_read_b128 v[136:139], v196 offset:18432
	ds_read_b128 v[106:109], v195 offset:16384
	ds_read_b128 v[110:113], v195 offset:18432
	ds_read_b128 v[114:117], v195 offset:20480
	ds_read_b128 v[118:121], v195 offset:22528
	ds_read_b128 v[140:143], v197 offset:16384
	ds_read_b128 v[144:147], v197 offset:18432
	s_waitcnt lgkmcnt(7)
	s_add_u32 m0, s12, 0xa000
	v_mfma_f32_16x16x32_f16 v[124:127], v[90:93], v[132:135], v[124:127]
	global_load_lds_dwordx4 v190, s[10:11]
	v_mfma_f32_16x16x32_f16 v[44:47], v[94:97], v[132:135], v[44:47]
	v_mfma_f32_16x16x32_f16 v[28:31], v[98:101], v[132:135], v[28:31]
	v_mfma_f32_16x16x32_f16 v[12:15], v[102:105], v[132:135], v[12:15]
	s_waitcnt lgkmcnt(6)
	s_add_u32 m0, s12, 0xb000
	v_mfma_f32_16x16x32_f16 v[56:59], v[90:93], v[136:139], v[56:59]
	global_load_lds_dwordx4 v192, s[10:11]
	v_mfma_f32_16x16x32_f16 v[40:43], v[94:97], v[136:139], v[40:43]
	v_mfma_f32_16x16x32_f16 v[24:27], v[98:101], v[136:139], v[24:27]
	v_mfma_f32_16x16x32_f16 v[8:11], v[102:105], v[136:139], v[8:11]
	s_waitcnt lgkmcnt(1)
	v_mfma_f32_16x16x32_f16 v[124:127], v[106:109], v[140:143], v[124:127]
	v_mfma_f32_16x16x32_f16 v[44:47], v[110:113], v[140:143], v[44:47]
	v_mfma_f32_16x16x32_f16 v[28:31], v[114:117], v[140:143], v[28:31]
	v_mfma_f32_16x16x32_f16 v[12:15], v[118:121], v[140:143], v[12:15]
	s_waitcnt lgkmcnt(0)
	v_mfma_f32_16x16x32_f16 v[56:59], v[106:109], v[144:147], v[56:59]
	v_mfma_f32_16x16x32_f16 v[40:43], v[110:113], v[144:147], v[40:43]
	v_mfma_f32_16x16x32_f16 v[24:27], v[114:117], v[144:147], v[24:27]
	v_mfma_f32_16x16x32_f16 v[8:11], v[118:121], v[144:147], v[8:11]
	s_add_u32 s10, s10, 128
	s_addc_u32 s11, s11, 0
	s_barrier
	ds_read_b128 v[174:177], v196 offset:24576
	ds_read_b128 v[178:181], v196 offset:26624
	ds_read_b128 v[182:185], v197 offset:24576
	ds_read_b128 v[186:189], v197 offset:26624
	s_waitcnt lgkmcnt(3)
	s_add_u32 m0, s12, 0xc000
	v_mfma_f32_16x16x32_f16 v[52:55], v[90:93], v[174:177], v[52:55]
	global_load_lds_dwordx4 v190, s[14:15]
	v_mfma_f32_16x16x32_f16 v[36:39], v[94:97], v[174:177], v[36:39]
	s_add_u32 m0, s12, 0xd000
	v_mfma_f32_16x16x32_f16 v[20:23], v[98:101], v[174:177], v[20:23]
	global_load_lds_dwordx4 v192, s[14:15]
	v_mfma_f32_16x16x32_f16 v[4:7], v[102:105], v[174:177], v[4:7]
	s_waitcnt lgkmcnt(2)
	s_add_u32 m0, s12, 0x4000
	v_mfma_f32_16x16x32_f16 v[48:51], v[90:93], v[178:181], v[48:51]
	global_load_lds_dwordx4 v190, s[8:9]
	v_mfma_f32_16x16x32_f16 v[32:35], v[94:97], v[178:181], v[32:35]
	s_add_u32 m0, s12, 0x5000
	v_mfma_f32_16x16x32_f16 v[16:19], v[98:101], v[178:181], v[16:19]
	global_load_lds_dwordx4 v191, s[8:9]
	v_mfma_f32_16x16x32_f16 v[0:3], v[102:105], v[178:181], v[0:3]
	s_waitcnt lgkmcnt(1)
	s_add_u32 m0, s12, 0x6000
	v_mfma_f32_16x16x32_f16 v[52:55], v[106:109], v[182:185], v[52:55]
	global_load_lds_dwordx4 v192, s[8:9]
	v_mfma_f32_16x16x32_f16 v[36:39], v[110:113], v[182:185], v[36:39]
	v_mfma_f32_16x16x32_f16 v[20:23], v[114:117], v[182:185], v[20:23]
	v_mfma_f32_16x16x32_f16 v[4:7], v[118:121], v[182:185], v[4:7]
	s_waitcnt lgkmcnt(0)
	s_add_u32 m0, s12, 0x7000
	v_mfma_f32_16x16x32_f16 v[48:51], v[106:109], v[186:189], v[48:51]
	global_load_lds_dwordx4 v193, s[8:9]
	v_mfma_f32_16x16x32_f16 v[32:35], v[110:113], v[186:189], v[32:35]
	v_mfma_f32_16x16x32_f16 v[16:19], v[114:117], v[186:189], v[16:19]
	v_mfma_f32_16x16x32_f16 v[0:3], v[118:121], v[186:189], v[0:3]
	s_add_u32 s14, s14, 128
	s_addc_u32 s15, s15, 0
	s_add_u32 s8, s8, 128
	s_addc_u32 s9, s9, 0
	s_waitcnt vmcnt(8)
	s_barrier
	ds_read_b128 v[90:93], v194 offset:0
	ds_read_b128 v[94:97], v194 offset:2048
	ds_read_b128 v[98:101], v194 offset:4096
	ds_read_b128 v[102:105], v194 offset:6144
	ds_read_b128 v[132:135], v196 offset:32768
	ds_read_b128 v[136:139], v196 offset:34816
	ds_read_b128 v[106:109], v195 offset:0
	ds_read_b128 v[110:113], v195 offset:2048
	ds_read_b128 v[114:117], v195 offset:4096
	ds_read_b128 v[118:121], v195 offset:6144
	ds_read_b128 v[140:143], v197 offset:32768
	ds_read_b128 v[144:147], v197 offset:34816
	s_waitcnt lgkmcnt(7)
	s_add_u32 m0, s12, 0xe000
	v_mfma_f32_16x16x32_f16 v[124:127], v[90:93], v[132:135], v[124:127]
	global_load_lds_dwordx4 v190, s[10:11]
	v_mfma_f32_16x16x32_f16 v[44:47], v[94:97], v[132:135], v[44:47]
	v_mfma_f32_16x16x32_f16 v[28:31], v[98:101], v[132:135], v[28:31]
	v_mfma_f32_16x16x32_f16 v[12:15], v[102:105], v[132:135], v[12:15]
	s_waitcnt lgkmcnt(6)
	s_add_u32 m0, s12, 0xf000
	v_mfma_f32_16x16x32_f16 v[56:59], v[90:93], v[136:139], v[56:59]
	global_load_lds_dwordx4 v192, s[10:11]
	v_mfma_f32_16x16x32_f16 v[40:43], v[94:97], v[136:139], v[40:43]
	v_mfma_f32_16x16x32_f16 v[24:27], v[98:101], v[136:139], v[24:27]
	v_mfma_f32_16x16x32_f16 v[8:11], v[102:105], v[136:139], v[8:11]
	s_waitcnt lgkmcnt(1)
	v_mfma_f32_16x16x32_f16 v[124:127], v[106:109], v[140:143], v[124:127]
	v_mfma_f32_16x16x32_f16 v[44:47], v[110:113], v[140:143], v[44:47]
	v_mfma_f32_16x16x32_f16 v[28:31], v[114:117], v[140:143], v[28:31]
	v_mfma_f32_16x16x32_f16 v[12:15], v[118:121], v[140:143], v[12:15]
	s_waitcnt lgkmcnt(0)
	v_mfma_f32_16x16x32_f16 v[56:59], v[106:109], v[144:147], v[56:59]
	v_mfma_f32_16x16x32_f16 v[40:43], v[110:113], v[144:147], v[40:43]
	v_mfma_f32_16x16x32_f16 v[24:27], v[114:117], v[144:147], v[24:27]
	v_mfma_f32_16x16x32_f16 v[8:11], v[118:121], v[144:147], v[8:11]
	s_add_u32 s10, s10, 128
	s_addc_u32 s11, s11, 0
	s_barrier
	ds_read_b128 v[174:177], v196 offset:0
	ds_read_b128 v[178:181], v196 offset:2048
	ds_read_b128 v[182:185], v197 offset:0
	ds_read_b128 v[186:189], v197 offset:2048
	s_waitcnt lgkmcnt(3)
	s_add_u32 m0, s12, 0x10000
	v_mfma_f32_16x16x32_f16 v[52:55], v[90:93], v[174:177], v[52:55]
	global_load_lds_dwordx4 v190, s[14:15]
	v_mfma_f32_16x16x32_f16 v[36:39], v[94:97], v[174:177], v[36:39]
	s_add_u32 m0, s12, 0x11000
	v_mfma_f32_16x16x32_f16 v[20:23], v[98:101], v[174:177], v[20:23]
	global_load_lds_dwordx4 v192, s[14:15]
	v_mfma_f32_16x16x32_f16 v[4:7], v[102:105], v[174:177], v[4:7]
	s_waitcnt lgkmcnt(2)
	s_add_u32 m0, s12, 0x0
	v_mfma_f32_16x16x32_f16 v[48:51], v[90:93], v[178:181], v[48:51]
	global_load_lds_dwordx4 v190, s[8:9]
	v_mfma_f32_16x16x32_f16 v[32:35], v[94:97], v[178:181], v[32:35]
	s_add_u32 m0, s12, 0x1000
	v_mfma_f32_16x16x32_f16 v[16:19], v[98:101], v[178:181], v[16:19]
	global_load_lds_dwordx4 v191, s[8:9]
	v_mfma_f32_16x16x32_f16 v[0:3], v[102:105], v[178:181], v[0:3]
	s_waitcnt lgkmcnt(1)
	s_add_u32 m0, s12, 0x2000
	v_mfma_f32_16x16x32_f16 v[52:55], v[106:109], v[182:185], v[52:55]
	global_load_lds_dwordx4 v192, s[8:9]
	v_mfma_f32_16x16x32_f16 v[36:39], v[110:113], v[182:185], v[36:39]
	v_mfma_f32_16x16x32_f16 v[20:23], v[114:117], v[182:185], v[20:23]
	v_mfma_f32_16x16x32_f16 v[4:7], v[118:121], v[182:185], v[4:7]
	s_waitcnt lgkmcnt(0)
	s_add_u32 m0, s12, 0x3000
	v_mfma_f32_16x16x32_f16 v[48:51], v[106:109], v[186:189], v[48:51]
	global_load_lds_dwordx4 v193, s[8:9]
	v_mfma_f32_16x16x32_f16 v[32:35], v[110:113], v[186:189], v[32:35]
	v_mfma_f32_16x16x32_f16 v[16:19], v[114:117], v[186:189], v[16:19]
	v_mfma_f32_16x16x32_f16 v[0:3], v[118:121], v[186:189], v[0:3]
	s_add_u32 s14, s14, 128
	s_addc_u32 s15, s15, 0
	s_add_u32 s8, s8, 128
	s_addc_u32 s9, s9, 0
	s_waitcnt vmcnt(8)
	s_barrier
	ds_read_b128 v[90:93], v194 offset:16384
	ds_read_b128 v[94:97], v194 offset:18432
	ds_read_b128 v[98:101], v194 offset:20480
	ds_read_b128 v[102:105], v194 offset:22528
	ds_read_b128 v[132:135], v196 offset:8192
	ds_read_b128 v[136:139], v196 offset:10240
	ds_read_b128 v[106:109], v195 offset:16384
	ds_read_b128 v[110:113], v195 offset:18432
	ds_read_b128 v[114:117], v195 offset:20480
	ds_read_b128 v[118:121], v195 offset:22528
	ds_read_b128 v[140:143], v197 offset:8192
	ds_read_b128 v[144:147], v197 offset:10240
	s_waitcnt lgkmcnt(7)
	s_add_u32 m0, s12, 0x8000
	v_mfma_f32_16x16x32_f16 v[124:127], v[90:93], v[132:135], v[124:127]
	global_load_lds_dwordx4 v190, s[10:11]
	v_mfma_f32_16x16x32_f16 v[44:47], v[94:97], v[132:135], v[44:47]
	v_mfma_f32_16x16x32_f16 v[28:31], v[98:101], v[132:135], v[28:31]
	v_mfma_f32_16x16x32_f16 v[12:15], v[102:105], v[132:135], v[12:15]
	s_waitcnt lgkmcnt(6)
	s_add_u32 m0, s12, 0x9000
	v_mfma_f32_16x16x32_f16 v[56:59], v[90:93], v[136:139], v[56:59]
	global_load_lds_dwordx4 v192, s[10:11]
	v_mfma_f32_16x16x32_f16 v[40:43], v[94:97], v[136:139], v[40:43]
	v_mfma_f32_16x16x32_f16 v[24:27], v[98:101], v[136:139], v[24:27]
	v_mfma_f32_16x16x32_f16 v[8:11], v[102:105], v[136:139], v[8:11]
	s_waitcnt lgkmcnt(1)
	v_mfma_f32_16x16x32_f16 v[124:127], v[106:109], v[140:143], v[124:127]
	v_mfma_f32_16x16x32_f16 v[44:47], v[110:113], v[140:143], v[44:47]
	v_mfma_f32_16x16x32_f16 v[28:31], v[114:117], v[140:143], v[28:31]
	v_mfma_f32_16x16x32_f16 v[12:15], v[118:121], v[140:143], v[12:15]
	s_waitcnt lgkmcnt(0)
	v_mfma_f32_16x16x32_f16 v[56:59], v[106:109], v[144:147], v[56:59]
	v_mfma_f32_16x16x32_f16 v[40:43], v[110:113], v[144:147], v[40:43]
	v_mfma_f32_16x16x32_f16 v[24:27], v[114:117], v[144:147], v[24:27]
	v_mfma_f32_16x16x32_f16 v[8:11], v[118:121], v[144:147], v[8:11]
	s_add_u32 s10, s10, 128
	s_addc_u32 s11, s11, 0
	s_barrier
	ds_read_b128 v[174:177], v196 offset:16384
	ds_read_b128 v[178:181], v196 offset:18432
	ds_read_b128 v[182:185], v197 offset:16384
	ds_read_b128 v[186:189], v197 offset:18432
	s_waitcnt lgkmcnt(3)
	s_add_u32 m0, s12, 0xa000
	v_mfma_f32_16x16x32_f16 v[52:55], v[90:93], v[174:177], v[52:55]
	global_load_lds_dwordx4 v190, s[14:15]
	v_mfma_f32_16x16x32_f16 v[36:39], v[94:97], v[174:177], v[36:39]
	s_add_u32 m0, s12, 0xb000
	v_mfma_f32_16x16x32_f16 v[20:23], v[98:101], v[174:177], v[20:23]
	global_load_lds_dwordx4 v192, s[14:15]
	v_mfma_f32_16x16x32_f16 v[4:7], v[102:105], v[174:177], v[4:7]
	s_waitcnt lgkmcnt(2)
	s_add_u32 m0, s12, 0x4000
	v_mfma_f32_16x16x32_f16 v[48:51], v[90:93], v[178:181], v[48:51]
	global_load_lds_dwordx4 v190, s[8:9]
	v_mfma_f32_16x16x32_f16 v[32:35], v[94:97], v[178:181], v[32:35]
	s_add_u32 m0, s12, 0x5000
	v_mfma_f32_16x16x32_f16 v[16:19], v[98:101], v[178:181], v[16:19]
	global_load_lds_dwordx4 v191, s[8:9]
	v_mfma_f32_16x16x32_f16 v[0:3], v[102:105], v[178:181], v[0:3]
	s_waitcnt lgkmcnt(1)
	s_add_u32 m0, s12, 0x6000
	v_mfma_f32_16x16x32_f16 v[52:55], v[106:109], v[182:185], v[52:55]
	global_load_lds_dwordx4 v192, s[8:9]
	v_mfma_f32_16x16x32_f16 v[36:39], v[110:113], v[182:185], v[36:39]
	v_mfma_f32_16x16x32_f16 v[20:23], v[114:117], v[182:185], v[20:23]
	v_mfma_f32_16x16x32_f16 v[4:7], v[118:121], v[182:185], v[4:7]
	s_waitcnt lgkmcnt(0)
	s_add_u32 m0, s12, 0x7000
	v_mfma_f32_16x16x32_f16 v[48:51], v[106:109], v[186:189], v[48:51]
	global_load_lds_dwordx4 v193, s[8:9]
	v_mfma_f32_16x16x32_f16 v[32:35], v[110:113], v[186:189], v[32:35]
	v_mfma_f32_16x16x32_f16 v[16:19], v[114:117], v[186:189], v[16:19]
	v_mfma_f32_16x16x32_f16 v[0:3], v[118:121], v[186:189], v[0:3]
	s_add_u32 s14, s14, 128
	s_addc_u32 s15, s15, 0
	s_add_u32 s8, s8, 128
	s_addc_u32 s9, s9, 0
	s_waitcnt vmcnt(8)
	s_barrier
	ds_read_b128 v[90:93], v194 offset:0
	ds_read_b128 v[94:97], v194 offset:2048
	ds_read_b128 v[98:101], v194 offset:4096
	ds_read_b128 v[102:105], v194 offset:6144
	ds_read_b128 v[132:135], v196 offset:24576
	ds_read_b128 v[136:139], v196 offset:26624
	ds_read_b128 v[106:109], v195 offset:0
	ds_read_b128 v[110:113], v195 offset:2048
	ds_read_b128 v[114:117], v195 offset:4096
	ds_read_b128 v[118:121], v195 offset:6144
	ds_read_b128 v[140:143], v197 offset:24576
	ds_read_b128 v[144:147], v197 offset:26624
	s_waitcnt lgkmcnt(7)
	s_add_u32 m0, s12, 0xc000
	v_mfma_f32_16x16x32_f16 v[124:127], v[90:93], v[132:135], v[124:127]
	global_load_lds_dwordx4 v190, s[10:11]
	v_mfma_f32_16x16x32_f16 v[44:47], v[94:97], v[132:135], v[44:47]
	v_mfma_f32_16x16x32_f16 v[28:31], v[98:101], v[132:135], v[28:31]
	v_mfma_f32_16x16x32_f16 v[12:15], v[102:105], v[132:135], v[12:15]
	s_waitcnt lgkmcnt(6)
	s_add_u32 m0, s12, 0xd000
	v_mfma_f32_16x16x32_f16 v[56:59], v[90:93], v[136:139], v[56:59]
	global_load_lds_dwordx4 v192, s[10:11]
	v_mfma_f32_16x16x32_f16 v[40:43], v[94:97], v[136:139], v[40:43]
	v_mfma_f32_16x16x32_f16 v[24:27], v[98:101], v[136:139], v[24:27]
	v_mfma_f32_16x16x32_f16 v[8:11], v[102:105], v[136:139], v[8:11]
	s_waitcnt lgkmcnt(1)
	v_mfma_f32_16x16x32_f16 v[124:127], v[106:109], v[140:143], v[124:127]
	v_mfma_f32_16x16x32_f16 v[44:47], v[110:113], v[140:143], v[44:47]
	v_mfma_f32_16x16x32_f16 v[28:31], v[114:117], v[140:143], v[28:31]
	v_mfma_f32_16x16x32_f16 v[12:15], v[118:121], v[140:143], v[12:15]
	s_waitcnt lgkmcnt(0)
	v_mfma_f32_16x16x32_f16 v[56:59], v[106:109], v[144:147], v[56:59]
	v_mfma_f32_16x16x32_f16 v[40:43], v[110:113], v[144:147], v[40:43]
	v_mfma_f32_16x16x32_f16 v[24:27], v[114:117], v[144:147], v[24:27]
	v_mfma_f32_16x16x32_f16 v[8:11], v[118:121], v[144:147], v[8:11]
	s_add_u32 s10, s10, 128
	s_addc_u32 s11, s11, 0
	s_barrier
	ds_read_b128 v[174:177], v196 offset:32768
	ds_read_b128 v[178:181], v196 offset:34816
	ds_read_b128 v[182:185], v197 offset:32768
	ds_read_b128 v[186:189], v197 offset:34816
	s_waitcnt lgkmcnt(3)
	s_add_u32 m0, s12, 0xe000
	v_mfma_f32_16x16x32_f16 v[52:55], v[90:93], v[174:177], v[52:55]
	global_load_lds_dwordx4 v190, s[14:15]
	v_mfma_f32_16x16x32_f16 v[36:39], v[94:97], v[174:177], v[36:39]
	s_add_u32 m0, s12, 0xf000
	v_mfma_f32_16x16x32_f16 v[20:23], v[98:101], v[174:177], v[20:23]
	global_load_lds_dwordx4 v192, s[14:15]
	v_mfma_f32_16x16x32_f16 v[4:7], v[102:105], v[174:177], v[4:7]
	s_waitcnt lgkmcnt(2)
	s_add_u32 m0, s12, 0x0
	v_mfma_f32_16x16x32_f16 v[48:51], v[90:93], v[178:181], v[48:51]
	global_load_lds_dwordx4 v190, s[8:9]
	v_mfma_f32_16x16x32_f16 v[32:35], v[94:97], v[178:181], v[32:35]
	s_add_u32 m0, s12, 0x1000
	v_mfma_f32_16x16x32_f16 v[16:19], v[98:101], v[178:181], v[16:19]
	global_load_lds_dwordx4 v191, s[8:9]
	v_mfma_f32_16x16x32_f16 v[0:3], v[102:105], v[178:181], v[0:3]
	s_waitcnt lgkmcnt(1)
	s_add_u32 m0, s12, 0x2000
	v_mfma_f32_16x16x32_f16 v[52:55], v[106:109], v[182:185], v[52:55]
	global_load_lds_dwordx4 v192, s[8:9]
	v_mfma_f32_16x16x32_f16 v[36:39], v[110:113], v[182:185], v[36:39]
	v_mfma_f32_16x16x32_f16 v[20:23], v[114:117], v[182:185], v[20:23]
	v_mfma_f32_16x16x32_f16 v[4:7], v[118:121], v[182:185], v[4:7]
	s_waitcnt lgkmcnt(0)
	s_add_u32 m0, s12, 0x3000
	v_mfma_f32_16x16x32_f16 v[48:51], v[106:109], v[186:189], v[48:51]
	global_load_lds_dwordx4 v193, s[8:9]
	v_mfma_f32_16x16x32_f16 v[32:35], v[110:113], v[186:189], v[32:35]
	v_mfma_f32_16x16x32_f16 v[16:19], v[114:117], v[186:189], v[16:19]
	v_mfma_f32_16x16x32_f16 v[0:3], v[118:121], v[186:189], v[0:3]
	s_add_u32 s14, s14, 128
	s_addc_u32 s15, s15, 0
	s_add_u32 s8, s8, 128
	s_addc_u32 s9, s9, 0
	s_waitcnt vmcnt(8)
	s_barrier
	ds_read_b128 v[90:93], v194 offset:16384
	ds_read_b128 v[94:97], v194 offset:18432
	ds_read_b128 v[98:101], v194 offset:20480
	ds_read_b128 v[102:105], v194 offset:22528
	ds_read_b128 v[132:135], v196 offset:0
	ds_read_b128 v[136:139], v196 offset:2048
	ds_read_b128 v[106:109], v195 offset:16384
	ds_read_b128 v[110:113], v195 offset:18432
	ds_read_b128 v[114:117], v195 offset:20480
	ds_read_b128 v[118:121], v195 offset:22528
	ds_read_b128 v[140:143], v197 offset:0
	ds_read_b128 v[144:147], v197 offset:2048
	s_waitcnt lgkmcnt(7)
	s_add_u32 m0, s12, 0x10000
	v_mfma_f32_16x16x32_f16 v[124:127], v[90:93], v[132:135], v[124:127]
	global_load_lds_dwordx4 v190, s[10:11]
	v_mfma_f32_16x16x32_f16 v[44:47], v[94:97], v[132:135], v[44:47]
	v_mfma_f32_16x16x32_f16 v[28:31], v[98:101], v[132:135], v[28:31]
	v_mfma_f32_16x16x32_f16 v[12:15], v[102:105], v[132:135], v[12:15]
	s_waitcnt lgkmcnt(6)
	s_add_u32 m0, s12, 0x11000
	v_mfma_f32_16x16x32_f16 v[56:59], v[90:93], v[136:139], v[56:59]
	global_load_lds_dwordx4 v192, s[10:11]
	v_mfma_f32_16x16x32_f16 v[40:43], v[94:97], v[136:139], v[40:43]
	v_mfma_f32_16x16x32_f16 v[24:27], v[98:101], v[136:139], v[24:27]
	v_mfma_f32_16x16x32_f16 v[8:11], v[102:105], v[136:139], v[8:11]
	s_waitcnt lgkmcnt(1)
	v_mfma_f32_16x16x32_f16 v[124:127], v[106:109], v[140:143], v[124:127]
	v_mfma_f32_16x16x32_f16 v[44:47], v[110:113], v[140:143], v[44:47]
	v_mfma_f32_16x16x32_f16 v[28:31], v[114:117], v[140:143], v[28:31]
	v_mfma_f32_16x16x32_f16 v[12:15], v[118:121], v[140:143], v[12:15]
	s_waitcnt lgkmcnt(0)
	v_mfma_f32_16x16x32_f16 v[56:59], v[106:109], v[144:147], v[56:59]
	v_mfma_f32_16x16x32_f16 v[40:43], v[110:113], v[144:147], v[40:43]
	v_mfma_f32_16x16x32_f16 v[24:27], v[114:117], v[144:147], v[24:27]
	v_mfma_f32_16x16x32_f16 v[8:11], v[118:121], v[144:147], v[8:11]
	s_add_u32 s10, s10, 128
	s_addc_u32 s11, s11, 0
	s_barrier
	ds_read_b128 v[174:177], v196 offset:8192
	ds_read_b128 v[178:181], v196 offset:10240
	ds_read_b128 v[182:185], v197 offset:8192
	ds_read_b128 v[186:189], v197 offset:10240
	s_waitcnt lgkmcnt(3)
	s_add_u32 m0, s12, 0x8000
	v_mfma_f32_16x16x32_f16 v[52:55], v[90:93], v[174:177], v[52:55]
	global_load_lds_dwordx4 v190, s[14:15]
	v_mfma_f32_16x16x32_f16 v[36:39], v[94:97], v[174:177], v[36:39]
	s_add_u32 m0, s12, 0x9000
	v_mfma_f32_16x16x32_f16 v[20:23], v[98:101], v[174:177], v[20:23]
	global_load_lds_dwordx4 v192, s[14:15]
	v_mfma_f32_16x16x32_f16 v[4:7], v[102:105], v[174:177], v[4:7]
	s_waitcnt lgkmcnt(2)
	s_add_u32 m0, s12, 0x4000
	v_mfma_f32_16x16x32_f16 v[48:51], v[90:93], v[178:181], v[48:51]
	global_load_lds_dwordx4 v190, s[8:9]
	v_mfma_f32_16x16x32_f16 v[32:35], v[94:97], v[178:181], v[32:35]
	s_add_u32 m0, s12, 0x5000
	v_mfma_f32_16x16x32_f16 v[16:19], v[98:101], v[178:181], v[16:19]
	global_load_lds_dwordx4 v191, s[8:9]
	v_mfma_f32_16x16x32_f16 v[0:3], v[102:105], v[178:181], v[0:3]
	s_waitcnt lgkmcnt(1)
	s_add_u32 m0, s12, 0x6000
	v_mfma_f32_16x16x32_f16 v[52:55], v[106:109], v[182:185], v[52:55]
	global_load_lds_dwordx4 v192, s[8:9]
	v_mfma_f32_16x16x32_f16 v[36:39], v[110:113], v[182:185], v[36:39]
	v_mfma_f32_16x16x32_f16 v[20:23], v[114:117], v[182:185], v[20:23]
	v_mfma_f32_16x16x32_f16 v[4:7], v[118:121], v[182:185], v[4:7]
	s_waitcnt lgkmcnt(0)
	s_add_u32 m0, s12, 0x7000
	v_mfma_f32_16x16x32_f16 v[48:51], v[106:109], v[186:189], v[48:51]
	global_load_lds_dwordx4 v193, s[8:9]
	v_mfma_f32_16x16x32_f16 v[32:35], v[110:113], v[186:189], v[32:35]
	v_mfma_f32_16x16x32_f16 v[16:19], v[114:117], v[186:189], v[16:19]
	v_mfma_f32_16x16x32_f16 v[0:3], v[118:121], v[186:189], v[0:3]
	s_add_u32 s14, s14, 128
	s_addc_u32 s15, s15, 0
	s_add_u32 s8, s8, 128
	s_addc_u32 s9, s9, 0
	s_waitcnt vmcnt(8)
	s_barrier
	ds_read_b128 v[90:93], v194 offset:0
	ds_read_b128 v[94:97], v194 offset:2048
	ds_read_b128 v[98:101], v194 offset:4096
	ds_read_b128 v[102:105], v194 offset:6144
	ds_read_b128 v[132:135], v196 offset:16384
	ds_read_b128 v[136:139], v196 offset:18432
	ds_read_b128 v[106:109], v195 offset:0
	ds_read_b128 v[110:113], v195 offset:2048
	ds_read_b128 v[114:117], v195 offset:4096
	ds_read_b128 v[118:121], v195 offset:6144
	ds_read_b128 v[140:143], v197 offset:16384
	ds_read_b128 v[144:147], v197 offset:18432
	s_waitcnt lgkmcnt(7)
	s_add_u32 m0, s12, 0xa000
	v_mfma_f32_16x16x32_f16 v[124:127], v[90:93], v[132:135], v[124:127]
	global_load_lds_dwordx4 v190, s[10:11]
	v_mfma_f32_16x16x32_f16 v[44:47], v[94:97], v[132:135], v[44:47]
	v_mfma_f32_16x16x32_f16 v[28:31], v[98:101], v[132:135], v[28:31]
	v_mfma_f32_16x16x32_f16 v[12:15], v[102:105], v[132:135], v[12:15]
	s_waitcnt lgkmcnt(6)
	s_add_u32 m0, s12, 0xb000
	v_mfma_f32_16x16x32_f16 v[56:59], v[90:93], v[136:139], v[56:59]
	global_load_lds_dwordx4 v192, s[10:11]
	v_mfma_f32_16x16x32_f16 v[40:43], v[94:97], v[136:139], v[40:43]
	v_mfma_f32_16x16x32_f16 v[24:27], v[98:101], v[136:139], v[24:27]
	v_mfma_f32_16x16x32_f16 v[8:11], v[102:105], v[136:139], v[8:11]
	s_waitcnt lgkmcnt(1)
	v_mfma_f32_16x16x32_f16 v[124:127], v[106:109], v[140:143], v[124:127]
	v_mfma_f32_16x16x32_f16 v[44:47], v[110:113], v[140:143], v[44:47]
	v_mfma_f32_16x16x32_f16 v[28:31], v[114:117], v[140:143], v[28:31]
	v_mfma_f32_16x16x32_f16 v[12:15], v[118:121], v[140:143], v[12:15]
	s_waitcnt lgkmcnt(0)
	v_mfma_f32_16x16x32_f16 v[56:59], v[106:109], v[144:147], v[56:59]
	v_mfma_f32_16x16x32_f16 v[40:43], v[110:113], v[144:147], v[40:43]
	v_mfma_f32_16x16x32_f16 v[24:27], v[114:117], v[144:147], v[24:27]
	v_mfma_f32_16x16x32_f16 v[8:11], v[118:121], v[144:147], v[8:11]
	s_add_u32 s10, s10, 128
	s_addc_u32 s11, s11, 0
	s_barrier
	ds_read_b128 v[174:177], v196 offset:24576
	ds_read_b128 v[178:181], v196 offset:26624
	ds_read_b128 v[182:185], v197 offset:24576
	ds_read_b128 v[186:189], v197 offset:26624
	s_waitcnt lgkmcnt(3)
	s_add_u32 m0, s12, 0xc000
	v_mfma_f32_16x16x32_f16 v[52:55], v[90:93], v[174:177], v[52:55]
	global_load_lds_dwordx4 v190, s[14:15]
	v_mfma_f32_16x16x32_f16 v[36:39], v[94:97], v[174:177], v[36:39]
	s_add_u32 m0, s12, 0xd000
	v_mfma_f32_16x16x32_f16 v[20:23], v[98:101], v[174:177], v[20:23]
	global_load_lds_dwordx4 v192, s[14:15]
	v_mfma_f32_16x16x32_f16 v[4:7], v[102:105], v[174:177], v[4:7]
	s_waitcnt lgkmcnt(2)
	s_add_u32 m0, s12, 0x0
	v_mfma_f32_16x16x32_f16 v[48:51], v[90:93], v[178:181], v[48:51]
	global_load_lds_dwordx4 v190, s[8:9]
	v_mfma_f32_16x16x32_f16 v[32:35], v[94:97], v[178:181], v[32:35]
	s_add_u32 m0, s12, 0x1000
	v_mfma_f32_16x16x32_f16 v[16:19], v[98:101], v[178:181], v[16:19]
	global_load_lds_dwordx4 v191, s[8:9]
	v_mfma_f32_16x16x32_f16 v[0:3], v[102:105], v[178:181], v[0:3]
	s_waitcnt lgkmcnt(1)
	s_add_u32 m0, s12, 0x2000
	v_mfma_f32_16x16x32_f16 v[52:55], v[106:109], v[182:185], v[52:55]
	global_load_lds_dwordx4 v192, s[8:9]
	v_mfma_f32_16x16x32_f16 v[36:39], v[110:113], v[182:185], v[36:39]
	v_mfma_f32_16x16x32_f16 v[20:23], v[114:117], v[182:185], v[20:23]
	v_mfma_f32_16x16x32_f16 v[4:7], v[118:121], v[182:185], v[4:7]
	s_waitcnt lgkmcnt(0)
	s_add_u32 m0, s12, 0x3000
	v_mfma_f32_16x16x32_f16 v[48:51], v[106:109], v[186:189], v[48:51]
	global_load_lds_dwordx4 v193, s[8:9]
	v_mfma_f32_16x16x32_f16 v[32:35], v[110:113], v[186:189], v[32:35]
	v_mfma_f32_16x16x32_f16 v[16:19], v[114:117], v[186:189], v[16:19]
	v_mfma_f32_16x16x32_f16 v[0:3], v[118:121], v[186:189], v[0:3]
	s_add_u32 s14, s14, 128
	s_addc_u32 s15, s15, 0
	s_add_u32 s8, s8, 128
	s_addc_u32 s9, s9, 0
	s_waitcnt vmcnt(8)
	s_barrier
	ds_read_b128 v[90:93], v194 offset:16384
	ds_read_b128 v[94:97], v194 offset:18432
	ds_read_b128 v[98:101], v194 offset:20480
	ds_read_b128 v[102:105], v194 offset:22528
	ds_read_b128 v[132:135], v196 offset:32768
	ds_read_b128 v[136:139], v196 offset:34816
	ds_read_b128 v[106:109], v195 offset:16384
	ds_read_b128 v[110:113], v195 offset:18432
	ds_read_b128 v[114:117], v195 offset:20480
	ds_read_b128 v[118:121], v195 offset:22528
	ds_read_b128 v[140:143], v197 offset:32768
	ds_read_b128 v[144:147], v197 offset:34816
	s_waitcnt lgkmcnt(7)
	s_add_u32 m0, s12, 0xe000
	v_mfma_f32_16x16x32_f16 v[124:127], v[90:93], v[132:135], v[124:127]
	global_load_lds_dwordx4 v190, s[10:11]
	v_mfma_f32_16x16x32_f16 v[44:47], v[94:97], v[132:135], v[44:47]
	v_mfma_f32_16x16x32_f16 v[28:31], v[98:101], v[132:135], v[28:31]
	v_mfma_f32_16x16x32_f16 v[12:15], v[102:105], v[132:135], v[12:15]
	s_waitcnt lgkmcnt(6)
	s_add_u32 m0, s12, 0xf000
	v_mfma_f32_16x16x32_f16 v[56:59], v[90:93], v[136:139], v[56:59]
	global_load_lds_dwordx4 v192, s[10:11]
	v_mfma_f32_16x16x32_f16 v[40:43], v[94:97], v[136:139], v[40:43]
	v_mfma_f32_16x16x32_f16 v[24:27], v[98:101], v[136:139], v[24:27]
	v_mfma_f32_16x16x32_f16 v[8:11], v[102:105], v[136:139], v[8:11]
	s_waitcnt lgkmcnt(1)
	v_mfma_f32_16x16x32_f16 v[124:127], v[106:109], v[140:143], v[124:127]
	v_mfma_f32_16x16x32_f16 v[44:47], v[110:113], v[140:143], v[44:47]
	v_mfma_f32_16x16x32_f16 v[28:31], v[114:117], v[140:143], v[28:31]
	v_mfma_f32_16x16x32_f16 v[12:15], v[118:121], v[140:143], v[12:15]
	s_waitcnt lgkmcnt(0)
	v_mfma_f32_16x16x32_f16 v[56:59], v[106:109], v[144:147], v[56:59]
	v_mfma_f32_16x16x32_f16 v[40:43], v[110:113], v[144:147], v[40:43]
	v_mfma_f32_16x16x32_f16 v[24:27], v[114:117], v[144:147], v[24:27]
	v_mfma_f32_16x16x32_f16 v[8:11], v[118:121], v[144:147], v[8:11]
	s_add_u32 s10, s10, 128
	s_addc_u32 s11, s11, 0
	s_barrier
	ds_read_b128 v[174:177], v196 offset:0
	ds_read_b128 v[178:181], v196 offset:2048
	ds_read_b128 v[182:185], v197 offset:0
	ds_read_b128 v[186:189], v197 offset:2048
	s_waitcnt lgkmcnt(3)
	s_add_u32 m0, s12, 0x10000
	v_mfma_f32_16x16x32_f16 v[52:55], v[90:93], v[174:177], v[52:55]
	global_load_lds_dwordx4 v190, s[14:15]
	v_mfma_f32_16x16x32_f16 v[36:39], v[94:97], v[174:177], v[36:39]
	s_add_u32 m0, s12, 0x11000
	v_mfma_f32_16x16x32_f16 v[20:23], v[98:101], v[174:177], v[20:23]
	global_load_lds_dwordx4 v192, s[14:15]
	v_mfma_f32_16x16x32_f16 v[4:7], v[102:105], v[174:177], v[4:7]
	s_waitcnt lgkmcnt(2)
	s_add_u32 m0, s12, 0x4000
	v_mfma_f32_16x16x32_f16 v[48:51], v[90:93], v[178:181], v[48:51]
	global_load_lds_dwordx4 v190, s[8:9]
	v_mfma_f32_16x16x32_f16 v[32:35], v[94:97], v[178:181], v[32:35]
	s_add_u32 m0, s12, 0x5000
	v_mfma_f32_16x16x32_f16 v[16:19], v[98:101], v[178:181], v[16:19]
	global_load_lds_dwordx4 v191, s[8:9]
	v_mfma_f32_16x16x32_f16 v[0:3], v[102:105], v[178:181], v[0:3]
	s_waitcnt lgkmcnt(1)
	s_add_u32 m0, s12, 0x6000
	v_mfma_f32_16x16x32_f16 v[52:55], v[106:109], v[182:185], v[52:55]
	global_load_lds_dwordx4 v192, s[8:9]
	v_mfma_f32_16x16x32_f16 v[36:39], v[110:113], v[182:185], v[36:39]
	v_mfma_f32_16x16x32_f16 v[20:23], v[114:117], v[182:185], v[20:23]
	v_mfma_f32_16x16x32_f16 v[4:7], v[118:121], v[182:185], v[4:7]
	s_waitcnt lgkmcnt(0)
	s_add_u32 m0, s12, 0x7000
	v_mfma_f32_16x16x32_f16 v[48:51], v[106:109], v[186:189], v[48:51]
	global_load_lds_dwordx4 v193, s[8:9]
	v_mfma_f32_16x16x32_f16 v[32:35], v[110:113], v[186:189], v[32:35]
	v_mfma_f32_16x16x32_f16 v[16:19], v[114:117], v[186:189], v[16:19]
	v_mfma_f32_16x16x32_f16 v[0:3], v[118:121], v[186:189], v[0:3]
	s_add_u32 s14, s14, 128
	s_addc_u32 s15, s15, 0
	s_add_u32 s8, s8, 128
	s_addc_u32 s9, s9, 0
	s_waitcnt vmcnt(8)
	s_barrier
	ds_read_b128 v[90:93], v194 offset:0
	ds_read_b128 v[94:97], v194 offset:2048
	ds_read_b128 v[98:101], v194 offset:4096
	ds_read_b128 v[102:105], v194 offset:6144
	ds_read_b128 v[132:135], v196 offset:8192
	ds_read_b128 v[136:139], v196 offset:10240
	ds_read_b128 v[106:109], v195 offset:0
	ds_read_b128 v[110:113], v195 offset:2048
	ds_read_b128 v[114:117], v195 offset:4096
	ds_read_b128 v[118:121], v195 offset:6144
	ds_read_b128 v[140:143], v197 offset:8192
	ds_read_b128 v[144:147], v197 offset:10240
	s_waitcnt lgkmcnt(7)
	s_add_u32 m0, s12, 0x8000
	v_mfma_f32_16x16x32_f16 v[124:127], v[90:93], v[132:135], v[124:127]
	global_load_lds_dwordx4 v190, s[10:11]
	v_mfma_f32_16x16x32_f16 v[44:47], v[94:97], v[132:135], v[44:47]
	v_mfma_f32_16x16x32_f16 v[28:31], v[98:101], v[132:135], v[28:31]
	v_mfma_f32_16x16x32_f16 v[12:15], v[102:105], v[132:135], v[12:15]
	s_waitcnt lgkmcnt(6)
	s_add_u32 m0, s12, 0x9000
	v_mfma_f32_16x16x32_f16 v[56:59], v[90:93], v[136:139], v[56:59]
	global_load_lds_dwordx4 v192, s[10:11]
	v_mfma_f32_16x16x32_f16 v[40:43], v[94:97], v[136:139], v[40:43]
	v_mfma_f32_16x16x32_f16 v[24:27], v[98:101], v[136:139], v[24:27]
	v_mfma_f32_16x16x32_f16 v[8:11], v[102:105], v[136:139], v[8:11]
	s_waitcnt lgkmcnt(1)
	v_mfma_f32_16x16x32_f16 v[124:127], v[106:109], v[140:143], v[124:127]
	v_mfma_f32_16x16x32_f16 v[44:47], v[110:113], v[140:143], v[44:47]
	v_mfma_f32_16x16x32_f16 v[28:31], v[114:117], v[140:143], v[28:31]
	v_mfma_f32_16x16x32_f16 v[12:15], v[118:121], v[140:143], v[12:15]
	s_waitcnt lgkmcnt(0)
	v_mfma_f32_16x16x32_f16 v[56:59], v[106:109], v[144:147], v[56:59]
	v_mfma_f32_16x16x32_f16 v[40:43], v[110:113], v[144:147], v[40:43]
	v_mfma_f32_16x16x32_f16 v[24:27], v[114:117], v[144:147], v[24:27]
	v_mfma_f32_16x16x32_f16 v[8:11], v[118:121], v[144:147], v[8:11]
	s_add_u32 s10, s10, 128
	s_addc_u32 s11, s11, 0
	s_barrier
	ds_read_b128 v[174:177], v196 offset:16384
	ds_read_b128 v[178:181], v196 offset:18432
	ds_read_b128 v[182:185], v197 offset:16384
	ds_read_b128 v[186:189], v197 offset:18432
	s_waitcnt lgkmcnt(3)
	s_add_u32 m0, s12, 0xa000
	v_mfma_f32_16x16x32_f16 v[52:55], v[90:93], v[174:177], v[52:55]
	global_load_lds_dwordx4 v190, s[14:15]
	v_mfma_f32_16x16x32_f16 v[36:39], v[94:97], v[174:177], v[36:39]
	s_add_u32 m0, s12, 0xb000
	v_mfma_f32_16x16x32_f16 v[20:23], v[98:101], v[174:177], v[20:23]
	global_load_lds_dwordx4 v192, s[14:15]
	v_mfma_f32_16x16x32_f16 v[4:7], v[102:105], v[174:177], v[4:7]
	s_waitcnt lgkmcnt(2)
	s_add_u32 m0, s12, 0x0
	v_mfma_f32_16x16x32_f16 v[48:51], v[90:93], v[178:181], v[48:51]
	global_load_lds_dwordx4 v190, s[8:9]
	v_mfma_f32_16x16x32_f16 v[32:35], v[94:97], v[178:181], v[32:35]
	s_add_u32 m0, s12, 0x1000
	v_mfma_f32_16x16x32_f16 v[16:19], v[98:101], v[178:181], v[16:19]
	global_load_lds_dwordx4 v191, s[8:9]
	v_mfma_f32_16x16x32_f16 v[0:3], v[102:105], v[178:181], v[0:3]
	s_waitcnt lgkmcnt(1)
	s_add_u32 m0, s12, 0x2000
	v_mfma_f32_16x16x32_f16 v[52:55], v[106:109], v[182:185], v[52:55]
	global_load_lds_dwordx4 v192, s[8:9]
	v_mfma_f32_16x16x32_f16 v[36:39], v[110:113], v[182:185], v[36:39]
	v_mfma_f32_16x16x32_f16 v[20:23], v[114:117], v[182:185], v[20:23]
	v_mfma_f32_16x16x32_f16 v[4:7], v[118:121], v[182:185], v[4:7]
	s_waitcnt lgkmcnt(0)
	s_add_u32 m0, s12, 0x3000
	v_mfma_f32_16x16x32_f16 v[48:51], v[106:109], v[186:189], v[48:51]
	global_load_lds_dwordx4 v193, s[8:9]
	v_mfma_f32_16x16x32_f16 v[32:35], v[110:113], v[186:189], v[32:35]
	v_mfma_f32_16x16x32_f16 v[16:19], v[114:117], v[186:189], v[16:19]
	v_mfma_f32_16x16x32_f16 v[0:3], v[118:121], v[186:189], v[0:3]
	s_add_u32 s14, s14, 128
	s_addc_u32 s15, s15, 0
	s_add_u32 s8, s8, 128
	s_addc_u32 s9, s9, 0
	s_waitcnt vmcnt(8)
	s_barrier
	ds_read_b128 v[90:93], v194 offset:16384
	ds_read_b128 v[94:97], v194 offset:18432
	ds_read_b128 v[98:101], v194 offset:20480
	ds_read_b128 v[102:105], v194 offset:22528
	ds_read_b128 v[132:135], v196 offset:24576
	ds_read_b128 v[136:139], v196 offset:26624
	ds_read_b128 v[106:109], v195 offset:16384
	ds_read_b128 v[110:113], v195 offset:18432
	ds_read_b128 v[114:117], v195 offset:20480
	ds_read_b128 v[118:121], v195 offset:22528
	ds_read_b128 v[140:143], v197 offset:24576
	ds_read_b128 v[144:147], v197 offset:26624
	s_waitcnt lgkmcnt(7)
	s_add_u32 m0, s12, 0xc000
	v_mfma_f32_16x16x32_f16 v[124:127], v[90:93], v[132:135], v[124:127]
	global_load_lds_dwordx4 v190, s[10:11]
	v_mfma_f32_16x16x32_f16 v[44:47], v[94:97], v[132:135], v[44:47]
	v_mfma_f32_16x16x32_f16 v[28:31], v[98:101], v[132:135], v[28:31]
	v_mfma_f32_16x16x32_f16 v[12:15], v[102:105], v[132:135], v[12:15]
	s_waitcnt lgkmcnt(6)
	s_add_u32 m0, s12, 0xd000
	v_mfma_f32_16x16x32_f16 v[56:59], v[90:93], v[136:139], v[56:59]
	global_load_lds_dwordx4 v192, s[10:11]
	v_mfma_f32_16x16x32_f16 v[40:43], v[94:97], v[136:139], v[40:43]
	v_mfma_f32_16x16x32_f16 v[24:27], v[98:101], v[136:139], v[24:27]
	v_mfma_f32_16x16x32_f16 v[8:11], v[102:105], v[136:139], v[8:11]
	s_waitcnt lgkmcnt(1)
	v_mfma_f32_16x16x32_f16 v[124:127], v[106:109], v[140:143], v[124:127]
	v_mfma_f32_16x16x32_f16 v[44:47], v[110:113], v[140:143], v[44:47]
	v_mfma_f32_16x16x32_f16 v[28:31], v[114:117], v[140:143], v[28:31]
	v_mfma_f32_16x16x32_f16 v[12:15], v[118:121], v[140:143], v[12:15]
	s_waitcnt lgkmcnt(0)
	v_mfma_f32_16x16x32_f16 v[56:59], v[106:109], v[144:147], v[56:59]
	v_mfma_f32_16x16x32_f16 v[40:43], v[110:113], v[144:147], v[40:43]
	v_mfma_f32_16x16x32_f16 v[24:27], v[114:117], v[144:147], v[24:27]
	v_mfma_f32_16x16x32_f16 v[8:11], v[118:121], v[144:147], v[8:11]
	s_add_u32 s10, s10, 128
	s_addc_u32 s11, s11, 0
	s_barrier
	ds_read_b128 v[174:177], v196 offset:32768
	ds_read_b128 v[178:181], v196 offset:34816
	ds_read_b128 v[182:185], v197 offset:32768
	ds_read_b128 v[186:189], v197 offset:34816
	s_waitcnt lgkmcnt(3)
	s_add_u32 m0, s12, 0xe000
	v_mfma_f32_16x16x32_f16 v[52:55], v[90:93], v[174:177], v[52:55]
	global_load_lds_dwordx4 v190, s[14:15]
	v_mfma_f32_16x16x32_f16 v[36:39], v[94:97], v[174:177], v[36:39]
	s_add_u32 m0, s12, 0xf000
	v_mfma_f32_16x16x32_f16 v[20:23], v[98:101], v[174:177], v[20:23]
	global_load_lds_dwordx4 v192, s[14:15]
	v_mfma_f32_16x16x32_f16 v[4:7], v[102:105], v[174:177], v[4:7]
	s_waitcnt lgkmcnt(2)
	s_add_u32 m0, s12, 0x4000
	v_mfma_f32_16x16x32_f16 v[48:51], v[90:93], v[178:181], v[48:51]
	global_load_lds_dwordx4 v190, s[8:9]
	v_mfma_f32_16x16x32_f16 v[32:35], v[94:97], v[178:181], v[32:35]
	s_add_u32 m0, s12, 0x5000
	v_mfma_f32_16x16x32_f16 v[16:19], v[98:101], v[178:181], v[16:19]
	global_load_lds_dwordx4 v191, s[8:9]
	v_mfma_f32_16x16x32_f16 v[0:3], v[102:105], v[178:181], v[0:3]
	s_waitcnt lgkmcnt(1)
	s_add_u32 m0, s12, 0x6000
	v_mfma_f32_16x16x32_f16 v[52:55], v[106:109], v[182:185], v[52:55]
	global_load_lds_dwordx4 v192, s[8:9]
	v_mfma_f32_16x16x32_f16 v[36:39], v[110:113], v[182:185], v[36:39]
	v_mfma_f32_16x16x32_f16 v[20:23], v[114:117], v[182:185], v[20:23]
	v_mfma_f32_16x16x32_f16 v[4:7], v[118:121], v[182:185], v[4:7]
	s_waitcnt lgkmcnt(0)
	s_add_u32 m0, s12, 0x7000
	v_mfma_f32_16x16x32_f16 v[48:51], v[106:109], v[186:189], v[48:51]
	global_load_lds_dwordx4 v193, s[8:9]
	v_mfma_f32_16x16x32_f16 v[32:35], v[110:113], v[186:189], v[32:35]
	v_mfma_f32_16x16x32_f16 v[16:19], v[114:117], v[186:189], v[16:19]
	v_mfma_f32_16x16x32_f16 v[0:3], v[118:121], v[186:189], v[0:3]
	s_add_u32 s14, s14, 128
	s_addc_u32 s15, s15, 0
	s_add_u32 s8, s8, 128
	s_addc_u32 s9, s9, 0
	s_add_i32 s13, s13, 1
	s_cmp_lt_u32 s13, 3
	s_cbranch_scc1 .Lgout_loop
	s_waitcnt vmcnt(8)
	s_barrier
	ds_read_b128 v[90:93], v194 offset:0
	ds_read_b128 v[94:97], v194 offset:2048
	ds_read_b128 v[98:101], v194 offset:4096
	ds_read_b128 v[102:105], v194 offset:6144
	ds_read_b128 v[132:135], v196 offset:0
	ds_read_b128 v[136:139], v196 offset:2048
	ds_read_b128 v[106:109], v195 offset:0
	ds_read_b128 v[110:113], v195 offset:2048
	ds_read_b128 v[114:117], v195 offset:4096
	ds_read_b128 v[118:121], v195 offset:6144
	ds_read_b128 v[140:143], v197 offset:0
	ds_read_b128 v[144:147], v197 offset:2048
	s_waitcnt lgkmcnt(7)
	v_mfma_f32_16x16x32_f16 v[124:127], v[90:93], v[132:135], v[124:127]
	v_mfma_f32_16x16x32_f16 v[44:47], v[94:97], v[132:135], v[44:47]
	v_mfma_f32_16x16x32_f16 v[28:31], v[98:101], v[132:135], v[28:31]
	v_mfma_f32_16x16x32_f16 v[12:15], v[102:105], v[132:135], v[12:15]
	s_waitcnt lgkmcnt(6)
	v_mfma_f32_16x16x32_f16 v[56:59], v[90:93], v[136:139], v[56:59]
	v_mfma_f32_16x16x32_f16 v[40:43], v[94:97], v[136:139], v[40:43]
	v_mfma_f32_16x16x32_f16 v[24:27], v[98:101], v[136:139], v[24:27]
	v_mfma_f32_16x16x32_f16 v[8:11], v[102:105], v[136:139], v[8:11]
	s_waitcnt lgkmcnt(1)
	v_mfma_f32_16x16x32_f16 v[124:127], v[106:109], v[140:143], v[124:127]
	v_mfma_f32_16x16x32_f16 v[44:47], v[110:113], v[140:143], v[44:47]
	v_mfma_f32_16x16x32_f16 v[28:31], v[114:117], v[140:143], v[28:31]
	v_mfma_f32_16x16x32_f16 v[12:15], v[118:121], v[140:143], v[12:15]
	s_waitcnt lgkmcnt(0)
	v_mfma_f32_16x16x32_f16 v[56:59], v[106:109], v[144:147], v[56:59]
	v_mfma_f32_16x16x32_f16 v[40:43], v[110:113], v[144:147], v[40:43]
	v_mfma_f32_16x16x32_f16 v[24:27], v[114:117], v[144:147], v[24:27]
	v_mfma_f32_16x16x32_f16 v[8:11], v[118:121], v[144:147], v[8:11]
	s_barrier
	ds_read_b128 v[174:177], v196 offset:8192
	ds_read_b128 v[178:181], v196 offset:10240
	ds_read_b128 v[182:185], v197 offset:8192
	ds_read_b128 v[186:189], v197 offset:10240
	s_waitcnt lgkmcnt(3)
	v_mfma_f32_16x16x32_f16 v[52:55], v[90:93], v[174:177], v[52:55]
	v_mfma_f32_16x16x32_f16 v[36:39], v[94:97], v[174:177], v[36:39]
	v_mfma_f32_16x16x32_f16 v[20:23], v[98:101], v[174:177], v[20:23]
	v_mfma_f32_16x16x32_f16 v[4:7], v[102:105], v[174:177], v[4:7]
	s_waitcnt lgkmcnt(2)
	v_mfma_f32_16x16x32_f16 v[48:51], v[90:93], v[178:181], v[48:51]
	v_mfma_f32_16x16x32_f16 v[32:35], v[94:97], v[178:181], v[32:35]
	v_mfma_f32_16x16x32_f16 v[16:19], v[98:101], v[178:181], v[16:19]
	v_mfma_f32_16x16x32_f16 v[0:3], v[102:105], v[178:181], v[0:3]
	s_waitcnt lgkmcnt(1)
	v_mfma_f32_16x16x32_f16 v[52:55], v[106:109], v[182:185], v[52:55]
	v_mfma_f32_16x16x32_f16 v[36:39], v[110:113], v[182:185], v[36:39]
	v_mfma_f32_16x16x32_f16 v[20:23], v[114:117], v[182:185], v[20:23]
	v_mfma_f32_16x16x32_f16 v[4:7], v[118:121], v[182:185], v[4:7]
	s_waitcnt lgkmcnt(0)
	v_mfma_f32_16x16x32_f16 v[48:51], v[106:109], v[186:189], v[48:51]
	v_mfma_f32_16x16x32_f16 v[32:35], v[110:113], v[186:189], v[32:35]
	v_mfma_f32_16x16x32_f16 v[16:19], v[114:117], v[186:189], v[16:19]
	v_mfma_f32_16x16x32_f16 v[0:3], v[118:121], v[186:189], v[0:3]
	s_waitcnt vmcnt(0)
	s_barrier
	ds_read_b128 v[90:93], v194 offset:16384
	ds_read_b128 v[94:97], v194 offset:18432
	ds_read_b128 v[98:101], v194 offset:20480
	ds_read_b128 v[102:105], v194 offset:22528
	ds_read_b128 v[132:135], v196 offset:16384
	ds_read_b128 v[136:139], v196 offset:18432
	ds_read_b128 v[106:109], v195 offset:16384
	ds_read_b128 v[110:113], v195 offset:18432
	ds_read_b128 v[114:117], v195 offset:20480
	ds_read_b128 v[118:121], v195 offset:22528
	ds_read_b128 v[140:143], v197 offset:16384
	ds_read_b128 v[144:147], v197 offset:18432
	s_waitcnt lgkmcnt(7)
	v_mfma_f32_16x16x32_f16 v[124:127], v[90:93], v[132:135], v[124:127]
	v_mfma_f32_16x16x32_f16 v[44:47], v[94:97], v[132:135], v[44:47]
	v_mfma_f32_16x16x32_f16 v[28:31], v[98:101], v[132:135], v[28:31]
	v_mfma_f32_16x16x32_f16 v[12:15], v[102:105], v[132:135], v[12:15]
	s_waitcnt lgkmcnt(6)
	v_mfma_f32_16x16x32_f16 v[56:59], v[90:93], v[136:139], v[56:59]
	v_mfma_f32_16x16x32_f16 v[40:43], v[94:97], v[136:139], v[40:43]
	v_mfma_f32_16x16x32_f16 v[24:27], v[98:101], v[136:139], v[24:27]
	v_mfma_f32_16x16x32_f16 v[8:11], v[102:105], v[136:139], v[8:11]
	s_waitcnt lgkmcnt(1)
	v_mfma_f32_16x16x32_f16 v[124:127], v[106:109], v[140:143], v[124:127]
	v_mfma_f32_16x16x32_f16 v[44:47], v[110:113], v[140:143], v[44:47]
	v_mfma_f32_16x16x32_f16 v[28:31], v[114:117], v[140:143], v[28:31]
	v_mfma_f32_16x16x32_f16 v[12:15], v[118:121], v[140:143], v[12:15]
	s_waitcnt lgkmcnt(0)
	v_mfma_f32_16x16x32_f16 v[56:59], v[106:109], v[144:147], v[56:59]
	v_mfma_f32_16x16x32_f16 v[40:43], v[110:113], v[144:147], v[40:43]
	v_mfma_f32_16x16x32_f16 v[24:27], v[114:117], v[144:147], v[24:27]
	v_mfma_f32_16x16x32_f16 v[8:11], v[118:121], v[144:147], v[8:11]
	s_barrier
	ds_read_b128 v[174:177], v196 offset:24576
	ds_read_b128 v[178:181], v196 offset:26624
	ds_read_b128 v[182:185], v197 offset:24576
	ds_read_b128 v[186:189], v197 offset:26624
	s_waitcnt lgkmcnt(3)
	v_mfma_f32_16x16x32_f16 v[52:55], v[90:93], v[174:177], v[52:55]
	v_mfma_f32_16x16x32_f16 v[36:39], v[94:97], v[174:177], v[36:39]
	v_mfma_f32_16x16x32_f16 v[20:23], v[98:101], v[174:177], v[20:23]
	v_mfma_f32_16x16x32_f16 v[4:7], v[102:105], v[174:177], v[4:7]
	s_waitcnt lgkmcnt(2)
	v_mfma_f32_16x16x32_f16 v[48:51], v[90:93], v[178:181], v[48:51]
	v_mfma_f32_16x16x32_f16 v[32:35], v[94:97], v[178:181], v[32:35]
	v_mfma_f32_16x16x32_f16 v[16:19], v[98:101], v[178:181], v[16:19]
	v_mfma_f32_16x16x32_f16 v[0:3], v[102:105], v[178:181], v[0:3]
	s_waitcnt lgkmcnt(1)
	v_mfma_f32_16x16x32_f16 v[52:55], v[106:109], v[182:185], v[52:55]
	v_mfma_f32_16x16x32_f16 v[36:39], v[110:113], v[182:185], v[36:39]
	v_mfma_f32_16x16x32_f16 v[20:23], v[114:117], v[182:185], v[20:23]
	v_mfma_f32_16x16x32_f16 v[4:7], v[118:121], v[182:185], v[4:7]
	s_waitcnt lgkmcnt(0)
	v_mfma_f32_16x16x32_f16 v[48:51], v[106:109], v[186:189], v[48:51]
	v_mfma_f32_16x16x32_f16 v[32:35], v[110:113], v[186:189], v[32:35]
	v_mfma_f32_16x16x32_f16 v[16:19], v[114:117], v[186:189], v[16:19]
	v_mfma_f32_16x16x32_f16 v[0:3], v[118:121], v[186:189], v[0:3]
	s_nop 7
	s_waitcnt vmcnt(0)
	v_pk_mul_f32 v[124:125], v[124:125], v[60:61]
	v_pk_mul_f32 v[126:127], v[126:127], v[62:63]
	v_pk_fma_f32 v[124:125], v[76:77], s[96:97], v[124:125] op_sel_hi:[1,0,1]
	v_pk_fma_f32 v[126:127], v[78:79], s[96:97], v[126:127] op_sel_hi:[1,0,1]
	global_store_dwordx4 v150, v[124:127], s[18:19] offset:0
	v_pk_mul_f32 v[44:45], v[44:45], v[64:65]
	v_pk_mul_f32 v[46:47], v[46:47], v[66:67]
	v_pk_fma_f32 v[44:45], v[80:81], s[96:97], v[44:45] op_sel_hi:[1,0,1]
	v_pk_fma_f32 v[46:47], v[82:83], s[96:97], v[46:47] op_sel_hi:[1,0,1]
	global_store_dwordx4 v150, v[44:47], s[18:19] offset:64
	v_pk_mul_f32 v[28:29], v[28:29], v[68:69]
	v_pk_mul_f32 v[30:31], v[30:31], v[70:71]
	v_pk_fma_f32 v[28:29], v[84:85], s[96:97], v[28:29] op_sel_hi:[1,0,1]
	v_pk_fma_f32 v[30:31], v[86:87], s[96:97], v[30:31] op_sel_hi:[1,0,1]
	global_store_dwordx4 v150, v[28:31], s[18:19] offset:128
	v_pk_mul_f32 v[12:13], v[12:13], v[72:73]
	v_pk_mul_f32 v[14:15], v[14:15], v[74:75]
	v_pk_fma_f32 v[12:13], v[200:201], s[96:97], v[12:13] op_sel_hi:[1,0,1]
	v_pk_fma_f32 v[14:15], v[202:203], s[96:97], v[14:15] op_sel_hi:[1,0,1]
	global_store_dwordx4 v150, v[12:15], s[18:19] offset:192
	v_pk_mul_f32 v[56:57], v[56:57], v[60:61]
	v_pk_mul_f32 v[58:59], v[58:59], v[62:63]
	v_pk_fma_f32 v[56:57], v[204:205], s[96:97], v[56:57] op_sel_hi:[1,0,1]
	v_pk_fma_f32 v[58:59], v[206:207], s[96:97], v[58:59] op_sel_hi:[1,0,1]
	global_store_dwordx4 v151, v[56:59], s[18:19] offset:0
	v_pk_mul_f32 v[40:41], v[40:41], v[64:65]
	v_pk_mul_f32 v[42:43], v[42:43], v[66:67]
	v_pk_fma_f32 v[40:41], v[210:211], s[96:97], v[40:41] op_sel_hi:[1,0,1]
	v_pk_fma_f32 v[42:43], v[212:213], s[96:97], v[42:43] op_sel_hi:[1,0,1]
	global_store_dwordx4 v151, v[40:43], s[18:19] offset:64
	v_pk_mul_f32 v[24:25], v[24:25], v[68:69]
	v_pk_mul_f32 v[26:27], v[26:27], v[70:71]
	v_pk_fma_f32 v[24:25], v[222:223], s[96:97], v[24:25] op_sel_hi:[1,0,1]
	v_pk_fma_f32 v[26:27], v[224:225], s[96:97], v[26:27] op_sel_hi:[1,0,1]
	global_store_dwordx4 v151, v[24:27], s[18:19] offset:128
	v_pk_mul_f32 v[8:9], v[8:9], v[72:73]
	v_pk_mul_f32 v[10:11], v[10:11], v[74:75]
	v_pk_fma_f32 v[8:9], v[226:227], s[96:97], v[8:9] op_sel_hi:[1,0,1]
	v_pk_fma_f32 v[10:11], v[228:229], s[96:97], v[10:11] op_sel_hi:[1,0,1]
	global_store_dwordx4 v151, v[8:11], s[18:19] offset:192
	v_pk_mul_f32 v[52:53], v[52:53], v[60:61]
	v_pk_mul_f32 v[54:55], v[54:55], v[62:63]
	v_pk_fma_f32 v[52:53], v[230:231], s[96:97], v[52:53] op_sel_hi:[1,0,1]
	v_pk_fma_f32 v[54:55], v[232:233], s[96:97], v[54:55] op_sel_hi:[1,0,1]
	global_store_dwordx4 v152, v[52:55], s[18:19] offset:0
	v_pk_mul_f32 v[36:37], v[36:37], v[64:65]
	v_pk_mul_f32 v[38:39], v[38:39], v[66:67]
	v_pk_fma_f32 v[36:37], v[234:235], s[96:97], v[36:37] op_sel_hi:[1,0,1]
	v_pk_fma_f32 v[38:39], v[236:237], s[96:97], v[38:39] op_sel_hi:[1,0,1]
	global_store_dwordx4 v152, v[36:39], s[18:19] offset:64
	v_pk_mul_f32 v[20:21], v[20:21], v[68:69]
	v_pk_mul_f32 v[22:23], v[22:23], v[70:71]
	v_pk_fma_f32 v[20:21], v[238:239], s[96:97], v[20:21] op_sel_hi:[1,0,1]
	v_pk_fma_f32 v[22:23], v[240:241], s[96:97], v[22:23] op_sel_hi:[1,0,1]
	global_store_dwordx4 v152, v[20:23], s[18:19] offset:128
	v_pk_mul_f32 v[4:5], v[4:5], v[72:73]
	v_pk_mul_f32 v[6:7], v[6:7], v[74:75]
	v_pk_fma_f32 v[4:5], v[242:243], s[96:97], v[4:5] op_sel_hi:[1,0,1]
	v_pk_fma_f32 v[6:7], v[244:245], s[96:97], v[6:7] op_sel_hi:[1,0,1]
	global_store_dwordx4 v152, v[4:7], s[18:19] offset:192
	v_pk_mul_f32 v[48:49], v[48:49], v[60:61]
	v_pk_mul_f32 v[50:51], v[50:51], v[62:63]
	v_pk_fma_f32 v[48:49], v[246:247], s[96:97], v[48:49] op_sel_hi:[1,0,1]
	v_pk_fma_f32 v[50:51], v[248:249], s[96:97], v[50:51] op_sel_hi:[1,0,1]
	global_store_dwordx4 v153, v[48:51], s[18:19] offset:0
	v_pk_mul_f32 v[32:33], v[32:33], v[64:65]
	v_pk_mul_f32 v[34:35], v[34:35], v[66:67]
	v_pk_fma_f32 v[32:33], v[158:159], s[96:97], v[32:33] op_sel_hi:[1,0,1]
	v_pk_fma_f32 v[34:35], v[160:161], s[96:97], v[34:35] op_sel_hi:[1,0,1]
	global_store_dwordx4 v153, v[32:35], s[18:19] offset:64
	v_pk_mul_f32 v[16:17], v[16:17], v[68:69]
	v_pk_mul_f32 v[18:19], v[18:19], v[70:71]
	v_pk_fma_f32 v[16:17], v[162:163], s[96:97], v[16:17] op_sel_hi:[1,0,1]
	v_pk_fma_f32 v[18:19], v[164:165], s[96:97], v[18:19] op_sel_hi:[1,0,1]
	global_store_dwordx4 v153, v[16:19], s[18:19] offset:128
	v_pk_mul_f32 v[0:1], v[0:1], v[72:73]
	v_pk_mul_f32 v[2:3], v[2:3], v[74:75]
	v_pk_fma_f32 v[0:1], v[154:155], s[96:97], v[0:1] op_sel_hi:[1,0,1]
	v_pk_fma_f32 v[2:3], v[156:157], s[96:97], v[2:3] op_sel_hi:[1,0,1]
	global_store_dwordx4 v153, v[0:3], s[18:19] offset:192
	s_add_i32 s6, s6, 1
	s_lshl_b32 s0, s6, 3
	v_readlane_b32 s4, v254, 36
	s_or_b32 s0, s0, s4
	v_readlane_b32 s4, v254, 37
	s_mul_i32 s0, s0, s4
	v_readlane_b32 s4, v254, 38
	s_add_i32 s0, s0, s4
	s_cmpk_gt_u32 s0, 0x5ff
	s_cbranch_scc1 .LBB0_1481
	s_branch .LBB0_1352
